# hand-written FoX page loop: transposed DPP butterfly reduction, per-lane softmax, row_newbcast broadcasts, canonical load order with counted waits
# speedup vs baseline: 1.1192x; 1.0031x over previous
.LBB0_322:
	v_mov_b32_e32 v120, v158
	s_load_dwordx2 s[4:5], s[42:43], 0x40
	s_load_dwordx2 s[2:3], s[42:43], 0x100
	s_ashr_i32 s41, s40, 31
	s_ashr_i32 s1, s40, 6
	s_lshl_b64 s[6:7], s[40:41], 2
	s_waitcnt lgkmcnt(0)
	s_add_u32 s4, s4, s6
	s_addc_u32 s5, s5, s7
	global_load_dword v4, v1, s[4:5]
	s_load_dwordx4 s[4:7], s[42:43], 0x10
	s_load_dwordx2 s[8:9], s[42:43], 0x20
	s_mul_i32 s11, s74, 0xa00
	s_mul_i32 s10, s1, 0x5800
	v_ashrrev_i32_e32 v160, 4, v120
	v_lshlrev_b32_e32 v2, 6, v160
	v_ashrrev_i32_e32 v3, 31, v2
	v_lshlrev_b64 v[2:3], 1, v[2:3]
	v_and_b32_e32 v159, 15, v120
	v_lshlrev_b32_e32 v0, 3, v159
	v_ashrrev_i32_e32 v121, 31, v120
	s_mov_b32 s38, s14
	s_mov_b32 s39, s14
	v_lshlrev_b32_e32 v161, 4, v120
	s_mov_b32 s22, 0x1e400
	s_mov_b32 s28, 0x1d000
	s_mov_b32 s29, 0x1d400
	s_mov_b32 s35, 0x1d800
	s_mov_b32 s41, 0x1dc00
	v_lshlrev_b32_e32 v162, 2, v160
	v_mov_b32_e32 v118, 0
	s_mov_b32 s15, s14
	s_mov_b32 s19, s14
	v_mov_b32_e32 v151, 0xf149f2ca
	v_mov_b32_e32 v124, v118
	v_mov_b32_e32 v125, v118
	v_mov_b32_e32 v128, v118
	v_mov_b32_e32 v129, v118
	v_mov_b32_e32 v126, v118
	v_mov_b32_e32 v127, v118
	v_mov_b32_e32 v132, v118
	v_mov_b32_e32 v133, v118
	v_mov_b32_e32 v130, v118
	v_mov_b32_e32 v131, v118
	v_mov_b32_e32 v150, 0xf149f2ca
	v_mov_b32_e32 v144, 0xf149f2ca
	v_mov_b32_e32 v142, 0xf149f2ca
	s_waitcnt vmcnt(0)
	v_readfirstlane_b32 s0, v4
	s_add_i32 s16, s0, s11
	s_ashr_i32 s17, s16, 31
	s_lshl_b64 s[24:25], s[16:17], 17
	s_waitcnt lgkmcnt(0)
	s_add_u32 s12, s4, s24
	s_addc_u32 s0, s5, s25
	s_and_b32 s13, s0, 0xffff
	s_add_u32 s4, s6, s24
	s_addc_u32 s0, s7, s25
	s_lshl_b64 s[6:7], s[16:17], 11
	s_and_b32 s5, s0, 0xffff
	s_add_u32 s16, s8, s6
	s_addc_u32 s6, s9, s7
	s_lshl_b32 s8, s1, 2
	s_and_b32 s0, s40, 63
	s_add_i32 s7, s10, 0x5800000
	s_and_b32 s17, s6, 0xffff
	s_add_i32 s6, s8, 0x4000
	s_mul_hi_i32 s9, s6, 0x1600
	s_add_u32 s6, s2, s7
	s_addc_u32 s7, s3, s9
	s_add_i32 s9, s8, 0x4001
	s_add_i32 s11, s10, 0x5801600
	v_lshl_add_u64 v[4:5], s[6:7], 0, v[2:3]
	s_mul_hi_i32 s7, s9, 0x1600
	s_add_u32 s6, s2, s11
	s_addc_u32 s7, s3, s7
	s_add_i32 s9, s8, 0x4002
	s_add_i32 s10, s10, 0x5802c00
	v_lshl_add_u64 v[4:5], v[4:5], 0, v[0:1]
	s_mov_b32 s11, 0xb600000
	v_lshl_add_u64 v[6:7], s[6:7], 0, v[2:3]
	s_mul_hi_i32 s7, s9, 0x1600
	s_add_u32 s6, s2, s10
	v_add_co_u32_e32 v4, vcc, s11, v4
	s_addc_u32 s7, s3, s7
	s_addk_i32 s8, 0x4003
	v_addc_co_u32_e32 v5, vcc, 0, v5, vcc
	v_lshl_add_u64 v[6:7], v[6:7], 0, v[0:1]
	v_lshl_add_u64 v[8:9], s[6:7], 0, v[2:3]
	s_mul_hi_i32 s7, s8, 0x1600
	s_mulk_i32 s8, 0x1600
	v_add_co_u32_e32 v6, vcc, s11, v6
	s_add_u32 s6, s2, s8
	s_nop 0
	v_addc_co_u32_e32 v7, vcc, 0, v7, vcc
	v_lshl_add_u64 v[8:9], v[8:9], 0, v[0:1]
	s_addc_u32 s7, s3, s7
	s_add_i32 s8, s1, s20
	v_add_co_u32_e32 v8, vcc, s11, v8
	v_lshl_add_u64 v[2:3], s[6:7], 0, v[2:3]
	s_ashr_i32 s9, s8, 31
	v_addc_co_u32_e32 v9, vcc, 0, v9, vcc
	v_lshl_add_u64 v[2:3], v[2:3], 0, v[0:1]
	s_lshl_b64 s[6:7], s[8:9], 10
	v_add_co_u32_e32 v2, vcc, s11, v2
	s_add_u32 s2, s2, s6
	s_nop 0
	v_addc_co_u32_e32 v3, vcc, 0, v3, vcc
	s_addc_u32 s3, s3, s7
	global_load_dwordx2 v[106:107], v[4:5], off offset:2560
	global_load_dwordx2 v[104:105], v[6:7], off offset:2560
	global_load_dwordx2 v[102:103], v[8:9], off offset:2560
	global_load_dwordx2 v[122:123], v[2:3], off offset:2560
	v_lshl_add_u64 v[2:3], v[120:121], 4, s[2:3]
	s_mov_b32 s1, 0x3080000
	v_add_co_u32_e32 v2, vcc, s1, v2
	s_mov_b32 s36, s12
	s_nop 0
	v_addc_co_u32_e32 v3, vcc, 0, v3, vcc
	global_load_dwordx4 v[98:101], v[2:3], off
	s_mov_b32 s37, s13
	s_mov_b32 s3, 0x1f400
	s_mov_b32 s8, 0x1f800
	s_mov_b32 s2, 0x1f000
	s_mov_b32 s1, 0x1e000
	s_mov_b32 s9, 0x1fc00
	s_mov_b32 s24, 0x1e800
	s_mov_b32 s25, 0x1ec00
	s_mov_b32 s6, s14
	s_mov_b32 s7, s14
	s_mov_b32 s10, s18
	s_mov_b32 s11, s14
	buffer_load_dwordx4 v[50:53], v161, s[36:39], s2 offen nt
	buffer_load_dwordx4 v[22:25], v161, s[4:7], s2 offen nt
	s_movk_i32 s10, 0x7c0
	buffer_load_dword v167, v162, s[16:19], s10 offen
	buffer_load_dwordx4 v[58:61], v161, s[36:39], s3 offen nt
	buffer_load_dwordx4 v[18:21], v161, s[4:7], s3 offen nt
	s_movk_i32 s10, 0x7d0
	buffer_load_dword v169, v162, s[16:19], s10 offen
	buffer_load_dwordx4 v[54:57], v161, s[36:39], s8 offen nt
	buffer_load_dwordx4 v[26:29], v161, s[4:7], s8 offen nt
	s_movk_i32 s10, 0x7e0
	buffer_load_dword v170, v162, s[16:19], s10 offen
	buffer_load_dwordx4 v[62:65], v161, s[36:39], s9 offen nt
	buffer_load_dwordx4 v[30:33], v161, s[4:7], s9 offen nt
	s_movk_i32 s10, 0x7f0
	buffer_load_dword v171, v162, s[16:19], s10 offen
	buffer_load_dwordx4 v[34:37], v161, s[36:39], s1 offen nt
	buffer_load_dwordx4 v[2:5], v161, s[4:7], s1 offen nt
	s_movk_i32 s10, 0x780
	buffer_load_dword v168, v162, s[16:19], s10 offen
	buffer_load_dwordx4 v[42:45], v161, s[36:39], s22 offen nt
	buffer_load_dwordx4 v[6:9], v161, s[4:7], s22 offen nt
	s_movk_i32 s10, 0x790
	buffer_load_dword v164, v162, s[16:19], s10 offen
	buffer_load_dwordx4 v[38:41], v161, s[36:39], s24 offen nt
	buffer_load_dwordx4 v[10:13], v161, s[4:7], s24 offen nt
	s_movk_i32 s10, 0x7a0
	buffer_load_dword v165, v162, s[16:19], s10 offen
	buffer_load_dwordx4 v[46:49], v161, s[36:39], s25 offen nt
	buffer_load_dwordx4 v[14:17], v161, s[4:7], s25 offen nt
	s_movk_i32 s10, 0x7b0
	buffer_load_dword v166, v162, s[16:19], s10 offen
	buffer_load_dwordx4 v[82:85], v161, s[36:39], s28 offen nt
	buffer_load_dwordx4 v[66:69], v161, s[4:7], s28 offen nt
	s_movk_i32 s10, 0x740
	buffer_load_dword v163, v162, s[16:19], s10 offen
	buffer_load_dwordx4 v[86:89], v161, s[36:39], s29 offen nt
	buffer_load_dwordx4 v[70:73], v161, s[4:7], s29 offen nt
	s_movk_i32 s10, 0x750
	buffer_load_dword v143, v162, s[16:19], s10 offen
	buffer_load_dwordx4 v[90:93], v161, s[36:39], s35 offen nt
	buffer_load_dwordx4 v[74:77], v161, s[4:7], s35 offen nt
	s_movk_i32 s10, 0x760
	buffer_load_dword v145, v162, s[16:19], s10 offen
	buffer_load_dwordx4 v[94:97], v161, s[36:39], s41 offen nt
	buffer_load_dwordx4 v[78:81], v161, s[4:7], s41 offen nt
	s_movk_i32 s10, 0x770
	buffer_load_dword v172, v162, s[16:19], s10 offen
	v_cmp_lt_i32_e32 vcc, s0, v120
	v_lshlrev_b32_e32 v0, 2, v159
	s_waitcnt vmcnt(40)
	v_lshlrev_b32_e32 v114, 16, v106
	v_and_b32_e32 v115, 0xffff0000, v106
	v_lshlrev_b32_e32 v116, 16, v107
	v_and_b32_e32 v117, 0xffff0000, v107
	s_waitcnt vmcnt(39)
	v_lshlrev_b32_e32 v110, 16, v104
	v_and_b32_e32 v111, 0xffff0000, v104
	v_lshlrev_b32_e32 v112, 16, v105
	v_and_b32_e32 v113, 0xffff0000, v105
	s_waitcnt vmcnt(38)
	v_lshlrev_b32_e32 v106, 16, v102
	v_and_b32_e32 v107, 0xffff0000, v102
	v_lshlrev_b32_e32 v108, 16, v103
	s_waitcnt vmcnt(36)
	v_cndmask_b32_e32 v99, 0, v99, vcc
	v_cndmask_b32_e32 v98, 0, v98, vcc
	v_cndmask_b32_e32 v100, 0, v100, vcc
	v_add_f32_dpp v99, v99, v99 quad_perm:[1,0,3,2] row_mask:0xf bank_mask:0xf bound_ctrl:1
	v_cndmask_b32_e32 v101, 0, v101, vcc
	v_add_f32_dpp v98, v98, v98 quad_perm:[1,0,3,2] row_mask:0xf bank_mask:0xf bound_ctrl:1
	v_add_f32_dpp v99, v99, v99 quad_perm:[2,3,0,1] row_mask:0xf bank_mask:0xf bound_ctrl:1
	v_add_f32_dpp v100, v100, v100 quad_perm:[1,0,3,2] row_mask:0xf bank_mask:0xf bound_ctrl:1
	v_add_f32_dpp v101, v101, v101 quad_perm:[1,0,3,2] row_mask:0xf bank_mask:0xf bound_ctrl:1
	v_add_f32_dpp v98, v98, v98 quad_perm:[2,3,0,1] row_mask:0xf bank_mask:0xf bound_ctrl:1
	v_add_f32_dpp v99, v99, v99 row_half_mirror row_mask:0xf bank_mask:0xf bound_ctrl:1
	v_add_f32_dpp v100, v100, v100 quad_perm:[2,3,0,1] row_mask:0xf bank_mask:0xf bound_ctrl:1
	v_add_f32_dpp v101, v101, v101 quad_perm:[2,3,0,1] row_mask:0xf bank_mask:0xf bound_ctrl:1
	v_add_f32_dpp v98, v98, v98 row_half_mirror row_mask:0xf bank_mask:0xf bound_ctrl:1
	v_add_f32_dpp v99, v99, v99 row_mirror row_mask:0xf bank_mask:0xf bound_ctrl:1
	v_add_f32_dpp v100, v100, v100 row_half_mirror row_mask:0xf bank_mask:0xf bound_ctrl:1
	v_add_f32_dpp v101, v101, v101 row_half_mirror row_mask:0xf bank_mask:0xf bound_ctrl:1
	v_add_f32_dpp v98, v98, v98 row_mirror row_mask:0xf bank_mask:0xf bound_ctrl:1
	v_readlane_b32 s9, v99, 16
	v_readlane_b32 s22, v99, 48
	v_add_f32_dpp v100, v100, v100 row_mirror row_mask:0xf bank_mask:0xf bound_ctrl:1
	v_add_f32_dpp v119, v101, v101 row_mirror row_mask:0xf bank_mask:0xf bound_ctrl:1
	v_readlane_b32 s0, v98, 0
	v_readlane_b32 s10, v98, 16
	v_readlane_b32 s1, v98, 32
	v_readlane_b32 s11, v98, 48
	v_readlane_b32 s2, v99, 0
	v_readlane_b32 s3, v99, 32
	v_mov_b32_e32 v98, s9
	v_mov_b32_e32 v99, s22
	v_readlane_b32 s24, v100, 16
	v_readlane_b32 s25, v100, 48
	v_pk_add_f32 v[98:99], s[2:3], v[98:99]
	v_readlane_b32 s2, v119, 16
	v_readlane_b32 s3, v119, 48
	v_readlane_b32 s6, v100, 0
	v_readlane_b32 s7, v100, 32
	v_readlane_b32 s8, v119, 0
	v_mov_b32_e32 v100, s24
	v_mov_b32_e32 v101, s25
	v_add_f32_e32 v121, v98, v99
	v_readlane_b32 s9, v119, 32
	v_mov_b32_e32 v98, s2
	v_mov_b32_e32 v99, s3
	v_pk_add_f32 v[100:101], s[6:7], v[100:101]
	v_pk_add_f32 v[98:99], s[8:9], v[98:99]
	v_add_f32_e32 v100, v100, v101
	v_add_f32_e32 v98, v98, v99
	v_cmp_eq_u32_e32 vcc, 2, v160
	v_mov_b32_e32 v99, s11
	v_and_b32_e32 v109, 0xffff0000, v103
	v_cndmask_b32_e32 v98, v98, v100, vcc
	v_cmp_eq_u32_e32 vcc, 1, v160
	v_lshlrev_b32_e32 v102, 16, v122
	v_and_b32_e32 v103, 0xffff0000, v122
	v_cndmask_b32_e32 v100, v98, v121, vcc
	v_mov_b32_e32 v98, s10
	v_pk_add_f32 v[98:99], s[0:1], v[98:99]
	v_cmp_gt_u32_e32 vcc, 16, v120
	v_add_f32_e32 v98, v98, v99
	v_lshlrev_b32_e32 v104, 16, v123
	v_and_b32_e32 v105, 0xffff0000, v123
	v_cndmask_b32_e32 v146, v100, v98, vcc
	s_movk_i32 s2, 0x88
	s_movk_i32 s3, 0x680
	s_mov_b32 s8, 0x1a000
	v_mov_b32_e32 v119, v118
	v_mov_b32_e32 v120, v118
	v_mov_b32_e32 v121, v118
	v_mov_b32_e32 v122, v118
	v_mov_b32_e32 v123, v118
	v_mov_b32_e32 v98, v118
	v_mov_b32_e32 v99, v118
	v_mov_b32_e32 v100, v118
	v_mov_b32_e32 v101, v118
	s_mov_b32 s6, s14
	s_mov_b32 s7, s15
	v_and_b32_e32 v155, 1, v159
	v_and_b32_e32 v156, 2, v159
	v_cmp_ne_u32_e64 s[28:29], 0, v155
	v_cmp_ne_u32_e64 s[24:25], 0, v156
	v_mov_b32_e32 v118, 0
	v_mov_b32_e32 v119, 0
	v_mov_b32_e32 v120, 0
	v_mov_b32_e32 v121, 0
	v_mov_b32_e32 v122, 0
	v_mov_b32_e32 v123, 0
	v_mov_b32_e32 v124, 0
	v_mov_b32_e32 v125, 0
	v_mov_b32_e32 v126, 0
	v_mov_b32_e32 v127, 0
	v_mov_b32_e32 v128, 0
	v_mov_b32_e32 v129, 0
	v_mov_b32_e32 v130, 0
	v_mov_b32_e32 v131, 0
	v_mov_b32_e32 v132, 0
	v_mov_b32_e32 v133, 0
	v_mov_b32_e32 v134, 0xf149f2ca
	v_mov_b32_e32 v135, 0
.Lpg_loop:
	s_waitcnt vmcnt(24)
	v_pk_mul_f32 v[98:99], v[116:117], v[52:53]
	v_pk_mul_f32 v[100:101], v[116:117], v[60:61]
	v_pk_mul_f32 v[174:175], v[116:117], v[56:57]
	v_pk_mul_f32 v[176:177], v[116:117], v[64:65]
	v_pk_fma_f32 v[98:99], v[114:115], v[50:51], v[98:99]
	v_pk_fma_f32 v[100:101], v[114:115], v[58:59], v[100:101]
	v_pk_fma_f32 v[174:175], v[114:115], v[54:55], v[174:175]
	v_pk_fma_f32 v[176:177], v[114:115], v[62:63], v[176:177]
	v_add_f32_e32 v136, v98, v99
	v_add_f32_e32 v137, v100, v101
	v_add_f32_e32 v138, v174, v175
	v_add_f32_e32 v139, v176, v177
	v_pk_mul_f32 v[98:99], v[112:113], v[52:53]
	v_pk_mul_f32 v[100:101], v[112:113], v[60:61]
	v_pk_mul_f32 v[174:175], v[112:113], v[56:57]
	v_pk_mul_f32 v[176:177], v[112:113], v[64:65]
	v_pk_fma_f32 v[98:99], v[110:111], v[50:51], v[98:99]
	v_pk_fma_f32 v[100:101], v[110:111], v[58:59], v[100:101]
	v_pk_fma_f32 v[174:175], v[110:111], v[54:55], v[174:175]
	v_pk_fma_f32 v[176:177], v[110:111], v[62:63], v[176:177]
	v_add_f32_e32 v140, v98, v99
	v_add_f32_e32 v141, v100, v101
	v_add_f32_e32 v142, v174, v175
	v_add_f32_e32 v144, v176, v177
	v_pk_mul_f32 v[98:99], v[108:109], v[52:53]
	v_pk_mul_f32 v[100:101], v[108:109], v[60:61]
	v_pk_mul_f32 v[174:175], v[108:109], v[56:57]
	v_pk_mul_f32 v[176:177], v[108:109], v[64:65]
	v_pk_fma_f32 v[98:99], v[106:107], v[50:51], v[98:99]
	v_pk_fma_f32 v[100:101], v[106:107], v[58:59], v[100:101]
	v_pk_fma_f32 v[174:175], v[106:107], v[54:55], v[174:175]
	v_pk_fma_f32 v[176:177], v[106:107], v[62:63], v[176:177]
	v_add_f32_e32 v147, v98, v99
	v_add_f32_e32 v148, v100, v101
	v_add_f32_e32 v149, v174, v175
	v_add_f32_e32 v150, v176, v177
	v_pk_mul_f32 v[98:99], v[104:105], v[52:53]
	v_pk_mul_f32 v[100:101], v[104:105], v[60:61]
	v_pk_mul_f32 v[174:175], v[104:105], v[56:57]
	v_pk_mul_f32 v[176:177], v[104:105], v[64:65]
	v_pk_fma_f32 v[98:99], v[102:103], v[50:51], v[98:99]
	v_pk_fma_f32 v[100:101], v[102:103], v[58:59], v[100:101]
	v_pk_fma_f32 v[174:175], v[102:103], v[54:55], v[174:175]
	v_pk_fma_f32 v[176:177], v[102:103], v[62:63], v[176:177]
	v_add_f32_e32 v151, v98, v99
	v_add_f32_e32 v152, v100, v101
	v_add_f32_e32 v153, v174, v175
	v_add_f32_e32 v154, v176, v177
	v_add_f32_e32 v155, v146, v171
	v_add_f32_e32 v156, v155, v170
	v_add_f32_e32 v157, v156, v169
	v_add_f32_dpp v136, v136, v136 row_mirror row_mask:0xf bank_mask:0x3 bound_ctrl:1
	v_add_f32_dpp v137, v137, v137 row_mirror row_mask:0xf bank_mask:0x3 bound_ctrl:1
	v_add_f32_dpp v138, v138, v138 row_mirror row_mask:0xf bank_mask:0x3 bound_ctrl:1
	v_add_f32_dpp v139, v139, v139 row_mirror row_mask:0xf bank_mask:0x3 bound_ctrl:1
	v_add_f32_dpp v140, v140, v140 row_mirror row_mask:0xf bank_mask:0x3 bound_ctrl:1
	v_add_f32_dpp v141, v141, v141 row_mirror row_mask:0xf bank_mask:0x3 bound_ctrl:1
	v_add_f32_dpp v142, v142, v142 row_mirror row_mask:0xf bank_mask:0x3 bound_ctrl:1
	v_add_f32_dpp v144, v144, v144 row_mirror row_mask:0xf bank_mask:0x3 bound_ctrl:1
	v_add_f32_dpp v136, v147, v147 row_mirror row_mask:0xf bank_mask:0xc bound_ctrl:1
	v_add_f32_dpp v137, v148, v148 row_mirror row_mask:0xf bank_mask:0xc bound_ctrl:1
	v_add_f32_dpp v138, v149, v149 row_mirror row_mask:0xf bank_mask:0xc bound_ctrl:1
	v_add_f32_dpp v139, v150, v150 row_mirror row_mask:0xf bank_mask:0xc bound_ctrl:1
	v_add_f32_dpp v140, v151, v151 row_mirror row_mask:0xf bank_mask:0xc bound_ctrl:1
	v_add_f32_dpp v141, v152, v152 row_mirror row_mask:0xf bank_mask:0xc bound_ctrl:1
	v_add_f32_dpp v142, v153, v153 row_mirror row_mask:0xf bank_mask:0xc bound_ctrl:1
	v_add_f32_dpp v144, v154, v154 row_mirror row_mask:0xf bank_mask:0xc bound_ctrl:1
	v_add_f32_dpp v136, v136, v136 row_half_mirror row_mask:0xf bank_mask:0x5 bound_ctrl:1
	v_add_f32_dpp v137, v137, v137 row_half_mirror row_mask:0xf bank_mask:0x5 bound_ctrl:1
	v_add_f32_dpp v138, v138, v138 row_half_mirror row_mask:0xf bank_mask:0x5 bound_ctrl:1
	v_add_f32_dpp v139, v139, v139 row_half_mirror row_mask:0xf bank_mask:0x5 bound_ctrl:1
	v_add_f32_dpp v136, v140, v140 row_half_mirror row_mask:0xf bank_mask:0xa bound_ctrl:1
	v_add_f32_dpp v137, v141, v141 row_half_mirror row_mask:0xf bank_mask:0xa bound_ctrl:1
	v_add_f32_dpp v138, v142, v142 row_half_mirror row_mask:0xf bank_mask:0xa bound_ctrl:1
	v_add_f32_dpp v139, v144, v144 row_half_mirror row_mask:0xf bank_mask:0xa bound_ctrl:1
	v_add_f32_dpp v136, v136, v136 quad_perm:[2,3,0,1] row_mask:0xf bank_mask:0xf bound_ctrl:1
	v_add_f32_dpp v138, v138, v138 quad_perm:[2,3,0,1] row_mask:0xf bank_mask:0xf bound_ctrl:1
	v_add_f32_dpp v137, v137, v137 quad_perm:[2,3,0,1] row_mask:0xf bank_mask:0xf bound_ctrl:1
	v_add_f32_dpp v139, v139, v139 quad_perm:[2,3,0,1] row_mask:0xf bank_mask:0xf bound_ctrl:1
	v_cndmask_b32_e64 v173, v155, v146, s[28:29]
	v_cndmask_b32_e64 v178, v157, v156, s[28:29]
	v_cndmask_b32_e64 v136, v136, v138, s[24:25]
	v_cndmask_b32_e64 v137, v137, v139, s[24:25]
	v_cndmask_b32_e64 v173, v178, v173, s[24:25]
	v_add_f32_e32 v146, v157, v167
	v_add_f32_dpp v136, v136, v136 quad_perm:[1,0,3,2] row_mask:0xf bank_mask:0xf bound_ctrl:1
	v_add_f32_dpp v137, v137, v137 quad_perm:[1,0,3,2] row_mask:0xf bank_mask:0xf bound_ctrl:1
	v_cndmask_b32_e64 v136, v136, v137, s[28:29]
	v_fmac_f32_e32 v136, 0x3fb8aa3b, v173
	s_nop 1
	v_max_f32_dpp v179, v136, v136 quad_perm:[1,0,3,2] row_mask:0xf bank_mask:0xf bound_ctrl:1
	s_nop 1
	v_max_f32_dpp v180, v179, v179 quad_perm:[2,3,0,1] row_mask:0xf bank_mask:0xf bound_ctrl:1
	v_max_f32_e32 v180, v134, v180
	v_sub_f32_e32 v155, v134, v180
	v_sub_f32_e32 v156, v136, v180
	v_mov_b32_e32 v134, v180
	v_exp_f32_e32 v155, v155
	v_exp_f32_e32 v156, v156
	s_nop 0
	v_mov_b32_dpp v137, v155 row_newbcast:0 row_mask:0xf bank_mask:0xf
	v_mov_b32_dpp v142, v155 row_newbcast:4 row_mask:0xf bank_mask:0xf
	v_mov_b32_dpp v150, v155 row_newbcast:8 row_mask:0xf bank_mask:0xf
	v_mov_b32_dpp v178, v155 row_newbcast:12 row_mask:0xf bank_mask:0xf
	v_add_f32_dpp v157, v156, v156 quad_perm:[1,0,3,2] row_mask:0xf bank_mask:0xf bound_ctrl:1
	v_mov_b32_dpp v138, v156 row_newbcast:0 row_mask:0xf bank_mask:0xf
	v_mov_b32_dpp v139, v156 row_newbcast:1 row_mask:0xf bank_mask:0xf
	v_mov_b32_dpp v140, v156 row_newbcast:2 row_mask:0xf bank_mask:0xf
	v_mov_b32_dpp v141, v156 row_newbcast:3 row_mask:0xf bank_mask:0xf
	v_add_f32_dpp v173, v157, v157 quad_perm:[2,3,0,1] row_mask:0xf bank_mask:0xf bound_ctrl:1
	v_mov_b32_dpp v144, v156 row_newbcast:4 row_mask:0xf bank_mask:0xf
	v_mov_b32_dpp v147, v156 row_newbcast:5 row_mask:0xf bank_mask:0xf
	v_mov_b32_dpp v148, v156 row_newbcast:6 row_mask:0xf bank_mask:0xf
	v_mov_b32_dpp v149, v156 row_newbcast:7 row_mask:0xf bank_mask:0xf
	v_fma_f32 v135, v135, v155, v173
	v_mov_b32_dpp v151, v156 row_newbcast:8 row_mask:0xf bank_mask:0xf
	v_mov_b32_dpp v152, v156 row_newbcast:9 row_mask:0xf bank_mask:0xf
	v_mov_b32_dpp v153, v156 row_newbcast:10 row_mask:0xf bank_mask:0xf
	v_mov_b32_dpp v154, v156 row_newbcast:11 row_mask:0xf bank_mask:0xf
	v_mov_b32_dpp v179, v156 row_newbcast:12 row_mask:0xf bank_mask:0xf
	v_mov_b32_dpp v180, v156 row_newbcast:13 row_mask:0xf bank_mask:0xf
	v_mov_b32_dpp v181, v156 row_newbcast:14 row_mask:0xf bank_mask:0xf
	v_mov_b32_dpp v0, v156 row_newbcast:15 row_mask:0xf bank_mask:0xf
	v_pk_mul_f32 v[118:119], v[118:119], v[136:137] op_sel:[0,1] op_sel_hi:[1,1]
	v_pk_mul_f32 v[120:121], v[120:121], v[136:137] op_sel:[0,1] op_sel_hi:[1,1]
	v_pk_mul_f32 v[122:123], v[122:123], v[142:143] op_sel:[0,0] op_sel_hi:[1,0]
	v_pk_mul_f32 v[124:125], v[124:125], v[142:143] op_sel:[0,0] op_sel_hi:[1,0]
	v_pk_mul_f32 v[126:127], v[126:127], v[150:151] op_sel:[0,0] op_sel_hi:[1,0]
	v_pk_mul_f32 v[128:129], v[128:129], v[150:151] op_sel:[0,0] op_sel_hi:[1,0]
	v_pk_mul_f32 v[130:131], v[130:131], v[178:179] op_sel:[0,0] op_sel_hi:[1,0]
	v_pk_mul_f32 v[132:133], v[132:133], v[178:179] op_sel:[0,0] op_sel_hi:[1,0]
	v_pk_fma_f32 v[118:119], v[138:139], v[22:23], v[118:119] op_sel:[0,0,0] op_sel_hi:[0,1,1]
	v_pk_fma_f32 v[120:121], v[138:139], v[24:25], v[120:121] op_sel:[0,0,0] op_sel_hi:[0,1,1]
	v_pk_fma_f32 v[122:123], v[144:145], v[22:23], v[122:123] op_sel:[0,0,0] op_sel_hi:[0,1,1]
	v_pk_fma_f32 v[124:125], v[144:145], v[24:25], v[124:125] op_sel:[0,0,0] op_sel_hi:[0,1,1]
	v_pk_fma_f32 v[126:127], v[150:151], v[22:23], v[126:127] op_sel:[1,0,0] op_sel_hi:[1,1,1]
	v_pk_fma_f32 v[128:129], v[150:151], v[24:25], v[128:129] op_sel:[1,0,0] op_sel_hi:[1,1,1]
	v_pk_fma_f32 v[130:131], v[178:179], v[22:23], v[130:131] op_sel:[1,0,0] op_sel_hi:[1,1,1]
	v_pk_fma_f32 v[132:133], v[178:179], v[24:25], v[132:133] op_sel:[1,0,0] op_sel_hi:[1,1,1]
	v_pk_fma_f32 v[118:119], v[138:139], v[18:19], v[118:119] op_sel:[1,0,0] op_sel_hi:[1,1,1]
	v_pk_fma_f32 v[120:121], v[138:139], v[20:21], v[120:121] op_sel:[1,0,0] op_sel_hi:[1,1,1]
	v_pk_fma_f32 v[122:123], v[146:147], v[18:19], v[122:123] op_sel:[1,0,0] op_sel_hi:[1,1,1]
	v_pk_fma_f32 v[124:125], v[146:147], v[20:21], v[124:125] op_sel:[1,0,0] op_sel_hi:[1,1,1]
	v_pk_fma_f32 v[126:127], v[152:153], v[18:19], v[126:127] op_sel:[0,0,0] op_sel_hi:[0,1,1]
	v_pk_fma_f32 v[128:129], v[152:153], v[20:21], v[128:129] op_sel:[0,0,0] op_sel_hi:[0,1,1]
	v_pk_fma_f32 v[130:131], v[180:181], v[18:19], v[130:131] op_sel:[0,0,0] op_sel_hi:[0,1,1]
	v_pk_fma_f32 v[132:133], v[180:181], v[20:21], v[132:133] op_sel:[0,0,0] op_sel_hi:[0,1,1]
	v_pk_fma_f32 v[118:119], v[140:141], v[26:27], v[118:119] op_sel:[0,0,0] op_sel_hi:[0,1,1]
	v_pk_fma_f32 v[120:121], v[140:141], v[28:29], v[120:121] op_sel:[0,0,0] op_sel_hi:[0,1,1]
	v_pk_fma_f32 v[122:123], v[148:149], v[26:27], v[122:123] op_sel:[0,0,0] op_sel_hi:[0,1,1]
	v_pk_fma_f32 v[124:125], v[148:149], v[28:29], v[124:125] op_sel:[0,0,0] op_sel_hi:[0,1,1]
	v_pk_fma_f32 v[126:127], v[152:153], v[26:27], v[126:127] op_sel:[1,0,0] op_sel_hi:[1,1,1]
	v_pk_fma_f32 v[128:129], v[152:153], v[28:29], v[128:129] op_sel:[1,0,0] op_sel_hi:[1,1,1]
	v_pk_fma_f32 v[130:131], v[180:181], v[26:27], v[130:131] op_sel:[1,0,0] op_sel_hi:[1,1,1]
	v_pk_fma_f32 v[132:133], v[180:181], v[28:29], v[132:133] op_sel:[1,0,0] op_sel_hi:[1,1,1]
	v_pk_fma_f32 v[118:119], v[140:141], v[30:31], v[118:119] op_sel:[1,0,0] op_sel_hi:[1,1,1]
	v_pk_fma_f32 v[120:121], v[140:141], v[32:33], v[120:121] op_sel:[1,0,0] op_sel_hi:[1,1,1]
	v_pk_fma_f32 v[122:123], v[148:149], v[30:31], v[122:123] op_sel:[1,0,0] op_sel_hi:[1,1,1]
	v_pk_fma_f32 v[124:125], v[148:149], v[32:33], v[124:125] op_sel:[1,0,0] op_sel_hi:[1,1,1]
	v_pk_fma_f32 v[126:127], v[154:155], v[30:31], v[126:127] op_sel:[0,0,0] op_sel_hi:[0,1,1]
	v_pk_fma_f32 v[128:129], v[154:155], v[32:33], v[128:129] op_sel:[0,0,0] op_sel_hi:[0,1,1]
	v_pk_fma_f32 v[130:131], v[0:1], v[30:31], v[130:131] op_sel:[0,0,0] op_sel_hi:[0,1,1]
	v_pk_fma_f32 v[132:133], v[0:1], v[32:33], v[132:133] op_sel:[0,0,0] op_sel_hi:[0,1,1]
	s_add_i32 s0, s8, 0x2000
	s_mov_b32 s6, s14
	s_mov_b32 s7, s15
	buffer_load_dwordx4 v[50:53], v161, s[12:15], s0 offen nt
	buffer_load_dwordx4 v[22:25], v161, s[4:7], s0 offen nt
	s_add_i32 s0, s3, 0x80
	buffer_load_dword v167, v162, s[16:19], s0 offen
	s_add_i32 s0, s8, 0x2400
	buffer_load_dwordx4 v[58:61], v161, s[12:15], s0 offen nt
	buffer_load_dwordx4 v[18:21], v161, s[4:7], s0 offen nt
	s_add_i32 s0, s3, 0x90
	buffer_load_dword v169, v162, s[16:19], s0 offen
	s_add_i32 s0, s8, 0x2800
	buffer_load_dwordx4 v[54:57], v161, s[12:15], s0 offen nt
	buffer_load_dwordx4 v[26:29], v161, s[4:7], s0 offen nt
	s_add_i32 s0, s3, 0xa0
	buffer_load_dword v170, v162, s[16:19], s0 offen
	s_add_i32 s0, s8, 0x2c00
	buffer_load_dwordx4 v[62:65], v161, s[12:15], s0 offen nt
	buffer_load_dwordx4 v[30:33], v161, s[4:7], s0 offen nt
	s_add_i32 s0, s3, 0xb0
	buffer_load_dword v171, v162, s[16:19], s0 offen
	s_waitcnt vmcnt(24)
	v_pk_mul_f32 v[98:99], v[116:117], v[36:37]
	v_pk_mul_f32 v[100:101], v[116:117], v[44:45]
	v_pk_mul_f32 v[174:175], v[116:117], v[40:41]
	v_pk_mul_f32 v[176:177], v[116:117], v[48:49]
	v_pk_fma_f32 v[98:99], v[114:115], v[34:35], v[98:99]
	v_pk_fma_f32 v[100:101], v[114:115], v[42:43], v[100:101]
	v_pk_fma_f32 v[174:175], v[114:115], v[38:39], v[174:175]
	v_pk_fma_f32 v[176:177], v[114:115], v[46:47], v[176:177]
	v_add_f32_e32 v136, v98, v99
	v_add_f32_e32 v137, v100, v101
	v_add_f32_e32 v138, v174, v175
	v_add_f32_e32 v139, v176, v177
	v_pk_mul_f32 v[98:99], v[112:113], v[36:37]
	v_pk_mul_f32 v[100:101], v[112:113], v[44:45]
	v_pk_mul_f32 v[174:175], v[112:113], v[40:41]
	v_pk_mul_f32 v[176:177], v[112:113], v[48:49]
	v_pk_fma_f32 v[98:99], v[110:111], v[34:35], v[98:99]
	v_pk_fma_f32 v[100:101], v[110:111], v[42:43], v[100:101]
	v_pk_fma_f32 v[174:175], v[110:111], v[38:39], v[174:175]
	v_pk_fma_f32 v[176:177], v[110:111], v[46:47], v[176:177]
	v_add_f32_e32 v140, v98, v99
	v_add_f32_e32 v141, v100, v101
	v_add_f32_e32 v142, v174, v175
	v_add_f32_e32 v144, v176, v177
	v_pk_mul_f32 v[98:99], v[108:109], v[36:37]
	v_pk_mul_f32 v[100:101], v[108:109], v[44:45]
	v_pk_mul_f32 v[174:175], v[108:109], v[40:41]
	v_pk_mul_f32 v[176:177], v[108:109], v[48:49]
	v_pk_fma_f32 v[98:99], v[106:107], v[34:35], v[98:99]
	v_pk_fma_f32 v[100:101], v[106:107], v[42:43], v[100:101]
	v_pk_fma_f32 v[174:175], v[106:107], v[38:39], v[174:175]
	v_pk_fma_f32 v[176:177], v[106:107], v[46:47], v[176:177]
	v_add_f32_e32 v147, v98, v99
	v_add_f32_e32 v148, v100, v101
	v_add_f32_e32 v149, v174, v175
	v_add_f32_e32 v150, v176, v177
	v_pk_mul_f32 v[98:99], v[104:105], v[36:37]
	v_pk_mul_f32 v[100:101], v[104:105], v[44:45]
	v_pk_mul_f32 v[174:175], v[104:105], v[40:41]
	v_pk_mul_f32 v[176:177], v[104:105], v[48:49]
	v_pk_fma_f32 v[98:99], v[102:103], v[34:35], v[98:99]
	v_pk_fma_f32 v[100:101], v[102:103], v[42:43], v[100:101]
	v_pk_fma_f32 v[174:175], v[102:103], v[38:39], v[174:175]
	v_pk_fma_f32 v[176:177], v[102:103], v[46:47], v[176:177]
	v_add_f32_e32 v151, v98, v99
	v_add_f32_e32 v152, v100, v101
	v_add_f32_e32 v153, v174, v175
	v_add_f32_e32 v154, v176, v177
	v_add_f32_e32 v155, v146, v166
	v_add_f32_e32 v156, v155, v165
	v_add_f32_e32 v157, v156, v164
	v_add_f32_dpp v136, v136, v136 row_mirror row_mask:0xf bank_mask:0x3 bound_ctrl:1
	v_add_f32_dpp v137, v137, v137 row_mirror row_mask:0xf bank_mask:0x3 bound_ctrl:1
	v_add_f32_dpp v138, v138, v138 row_mirror row_mask:0xf bank_mask:0x3 bound_ctrl:1
	v_add_f32_dpp v139, v139, v139 row_mirror row_mask:0xf bank_mask:0x3 bound_ctrl:1
	v_add_f32_dpp v140, v140, v140 row_mirror row_mask:0xf bank_mask:0x3 bound_ctrl:1
	v_add_f32_dpp v141, v141, v141 row_mirror row_mask:0xf bank_mask:0x3 bound_ctrl:1
	v_add_f32_dpp v142, v142, v142 row_mirror row_mask:0xf bank_mask:0x3 bound_ctrl:1
	v_add_f32_dpp v144, v144, v144 row_mirror row_mask:0xf bank_mask:0x3 bound_ctrl:1
	v_add_f32_dpp v136, v147, v147 row_mirror row_mask:0xf bank_mask:0xc bound_ctrl:1
	v_add_f32_dpp v137, v148, v148 row_mirror row_mask:0xf bank_mask:0xc bound_ctrl:1
	v_add_f32_dpp v138, v149, v149 row_mirror row_mask:0xf bank_mask:0xc bound_ctrl:1
	v_add_f32_dpp v139, v150, v150 row_mirror row_mask:0xf bank_mask:0xc bound_ctrl:1
	v_add_f32_dpp v140, v151, v151 row_mirror row_mask:0xf bank_mask:0xc bound_ctrl:1
	v_add_f32_dpp v141, v152, v152 row_mirror row_mask:0xf bank_mask:0xc bound_ctrl:1
	v_add_f32_dpp v142, v153, v153 row_mirror row_mask:0xf bank_mask:0xc bound_ctrl:1
	v_add_f32_dpp v144, v154, v154 row_mirror row_mask:0xf bank_mask:0xc bound_ctrl:1
	v_add_f32_dpp v136, v136, v136 row_half_mirror row_mask:0xf bank_mask:0x5 bound_ctrl:1
	v_add_f32_dpp v137, v137, v137 row_half_mirror row_mask:0xf bank_mask:0x5 bound_ctrl:1
	v_add_f32_dpp v138, v138, v138 row_half_mirror row_mask:0xf bank_mask:0x5 bound_ctrl:1
	v_add_f32_dpp v139, v139, v139 row_half_mirror row_mask:0xf bank_mask:0x5 bound_ctrl:1
	v_add_f32_dpp v136, v140, v140 row_half_mirror row_mask:0xf bank_mask:0xa bound_ctrl:1
	v_add_f32_dpp v137, v141, v141 row_half_mirror row_mask:0xf bank_mask:0xa bound_ctrl:1
	v_add_f32_dpp v138, v142, v142 row_half_mirror row_mask:0xf bank_mask:0xa bound_ctrl:1
	v_add_f32_dpp v139, v144, v144 row_half_mirror row_mask:0xf bank_mask:0xa bound_ctrl:1
	v_add_f32_dpp v136, v136, v136 quad_perm:[2,3,0,1] row_mask:0xf bank_mask:0xf bound_ctrl:1
	v_add_f32_dpp v138, v138, v138 quad_perm:[2,3,0,1] row_mask:0xf bank_mask:0xf bound_ctrl:1
	v_add_f32_dpp v137, v137, v137 quad_perm:[2,3,0,1] row_mask:0xf bank_mask:0xf bound_ctrl:1
	v_add_f32_dpp v139, v139, v139 quad_perm:[2,3,0,1] row_mask:0xf bank_mask:0xf bound_ctrl:1
	v_cndmask_b32_e64 v173, v155, v146, s[28:29]
	v_cndmask_b32_e64 v178, v157, v156, s[28:29]
	v_cndmask_b32_e64 v136, v136, v138, s[24:25]
	v_cndmask_b32_e64 v137, v137, v139, s[24:25]
	v_cndmask_b32_e64 v173, v178, v173, s[24:25]
	v_add_f32_e32 v146, v157, v168
	v_add_f32_dpp v136, v136, v136 quad_perm:[1,0,3,2] row_mask:0xf bank_mask:0xf bound_ctrl:1
	v_add_f32_dpp v137, v137, v137 quad_perm:[1,0,3,2] row_mask:0xf bank_mask:0xf bound_ctrl:1
	v_cndmask_b32_e64 v136, v136, v137, s[28:29]
	v_fmac_f32_e32 v136, 0x3fb8aa3b, v173
	s_nop 1
	v_max_f32_dpp v179, v136, v136 quad_perm:[1,0,3,2] row_mask:0xf bank_mask:0xf bound_ctrl:1
	s_nop 1
	v_max_f32_dpp v180, v179, v179 quad_perm:[2,3,0,1] row_mask:0xf bank_mask:0xf bound_ctrl:1
	v_max_f32_e32 v180, v134, v180
	v_sub_f32_e32 v155, v134, v180
	v_sub_f32_e32 v156, v136, v180
	v_mov_b32_e32 v134, v180
	v_exp_f32_e32 v155, v155
	v_exp_f32_e32 v156, v156
	s_nop 0
	v_mov_b32_dpp v137, v155 row_newbcast:0 row_mask:0xf bank_mask:0xf
	v_mov_b32_dpp v142, v155 row_newbcast:4 row_mask:0xf bank_mask:0xf
	v_mov_b32_dpp v150, v155 row_newbcast:8 row_mask:0xf bank_mask:0xf
	v_mov_b32_dpp v178, v155 row_newbcast:12 row_mask:0xf bank_mask:0xf
	v_add_f32_dpp v157, v156, v156 quad_perm:[1,0,3,2] row_mask:0xf bank_mask:0xf bound_ctrl:1
	v_mov_b32_dpp v138, v156 row_newbcast:0 row_mask:0xf bank_mask:0xf
	v_mov_b32_dpp v139, v156 row_newbcast:1 row_mask:0xf bank_mask:0xf
	v_mov_b32_dpp v140, v156 row_newbcast:2 row_mask:0xf bank_mask:0xf
	v_mov_b32_dpp v141, v156 row_newbcast:3 row_mask:0xf bank_mask:0xf
	v_add_f32_dpp v173, v157, v157 quad_perm:[2,3,0,1] row_mask:0xf bank_mask:0xf bound_ctrl:1
	v_mov_b32_dpp v144, v156 row_newbcast:4 row_mask:0xf bank_mask:0xf
	v_mov_b32_dpp v147, v156 row_newbcast:5 row_mask:0xf bank_mask:0xf
	v_mov_b32_dpp v148, v156 row_newbcast:6 row_mask:0xf bank_mask:0xf
	v_mov_b32_dpp v149, v156 row_newbcast:7 row_mask:0xf bank_mask:0xf
	v_fma_f32 v135, v135, v155, v173
	v_mov_b32_dpp v151, v156 row_newbcast:8 row_mask:0xf bank_mask:0xf
	v_mov_b32_dpp v152, v156 row_newbcast:9 row_mask:0xf bank_mask:0xf
	v_mov_b32_dpp v153, v156 row_newbcast:10 row_mask:0xf bank_mask:0xf
	v_mov_b32_dpp v154, v156 row_newbcast:11 row_mask:0xf bank_mask:0xf
	v_mov_b32_dpp v179, v156 row_newbcast:12 row_mask:0xf bank_mask:0xf
	v_mov_b32_dpp v180, v156 row_newbcast:13 row_mask:0xf bank_mask:0xf
	v_mov_b32_dpp v181, v156 row_newbcast:14 row_mask:0xf bank_mask:0xf
	v_mov_b32_dpp v0, v156 row_newbcast:15 row_mask:0xf bank_mask:0xf
	v_pk_mul_f32 v[118:119], v[118:119], v[136:137] op_sel:[0,1] op_sel_hi:[1,1]
	v_pk_mul_f32 v[120:121], v[120:121], v[136:137] op_sel:[0,1] op_sel_hi:[1,1]
	v_pk_mul_f32 v[122:123], v[122:123], v[142:143] op_sel:[0,0] op_sel_hi:[1,0]
	v_pk_mul_f32 v[124:125], v[124:125], v[142:143] op_sel:[0,0] op_sel_hi:[1,0]
	v_pk_mul_f32 v[126:127], v[126:127], v[150:151] op_sel:[0,0] op_sel_hi:[1,0]
	v_pk_mul_f32 v[128:129], v[128:129], v[150:151] op_sel:[0,0] op_sel_hi:[1,0]
	v_pk_mul_f32 v[130:131], v[130:131], v[178:179] op_sel:[0,0] op_sel_hi:[1,0]
	v_pk_mul_f32 v[132:133], v[132:133], v[178:179] op_sel:[0,0] op_sel_hi:[1,0]
	v_pk_fma_f32 v[118:119], v[138:139], v[2:3], v[118:119] op_sel:[0,0,0] op_sel_hi:[0,1,1]
	v_pk_fma_f32 v[120:121], v[138:139], v[4:5], v[120:121] op_sel:[0,0,0] op_sel_hi:[0,1,1]
	v_pk_fma_f32 v[122:123], v[144:145], v[2:3], v[122:123] op_sel:[0,0,0] op_sel_hi:[0,1,1]
	v_pk_fma_f32 v[124:125], v[144:145], v[4:5], v[124:125] op_sel:[0,0,0] op_sel_hi:[0,1,1]
	v_pk_fma_f32 v[126:127], v[150:151], v[2:3], v[126:127] op_sel:[1,0,0] op_sel_hi:[1,1,1]
	v_pk_fma_f32 v[128:129], v[150:151], v[4:5], v[128:129] op_sel:[1,0,0] op_sel_hi:[1,1,1]
	v_pk_fma_f32 v[130:131], v[178:179], v[2:3], v[130:131] op_sel:[1,0,0] op_sel_hi:[1,1,1]
	v_pk_fma_f32 v[132:133], v[178:179], v[4:5], v[132:133] op_sel:[1,0,0] op_sel_hi:[1,1,1]
	v_pk_fma_f32 v[118:119], v[138:139], v[6:7], v[118:119] op_sel:[1,0,0] op_sel_hi:[1,1,1]
	v_pk_fma_f32 v[120:121], v[138:139], v[8:9], v[120:121] op_sel:[1,0,0] op_sel_hi:[1,1,1]
	v_pk_fma_f32 v[122:123], v[146:147], v[6:7], v[122:123] op_sel:[1,0,0] op_sel_hi:[1,1,1]
	v_pk_fma_f32 v[124:125], v[146:147], v[8:9], v[124:125] op_sel:[1,0,0] op_sel_hi:[1,1,1]
	v_pk_fma_f32 v[126:127], v[152:153], v[6:7], v[126:127] op_sel:[0,0,0] op_sel_hi:[0,1,1]
	v_pk_fma_f32 v[128:129], v[152:153], v[8:9], v[128:129] op_sel:[0,0,0] op_sel_hi:[0,1,1]
	v_pk_fma_f32 v[130:131], v[180:181], v[6:7], v[130:131] op_sel:[0,0,0] op_sel_hi:[0,1,1]
	v_pk_fma_f32 v[132:133], v[180:181], v[8:9], v[132:133] op_sel:[0,0,0] op_sel_hi:[0,1,1]
	v_pk_fma_f32 v[118:119], v[140:141], v[10:11], v[118:119] op_sel:[0,0,0] op_sel_hi:[0,1,1]
	v_pk_fma_f32 v[120:121], v[140:141], v[12:13], v[120:121] op_sel:[0,0,0] op_sel_hi:[0,1,1]
	v_pk_fma_f32 v[122:123], v[148:149], v[10:11], v[122:123] op_sel:[0,0,0] op_sel_hi:[0,1,1]
	v_pk_fma_f32 v[124:125], v[148:149], v[12:13], v[124:125] op_sel:[0,0,0] op_sel_hi:[0,1,1]
	v_pk_fma_f32 v[126:127], v[152:153], v[10:11], v[126:127] op_sel:[1,0,0] op_sel_hi:[1,1,1]
	v_pk_fma_f32 v[128:129], v[152:153], v[12:13], v[128:129] op_sel:[1,0,0] op_sel_hi:[1,1,1]
	v_pk_fma_f32 v[130:131], v[180:181], v[10:11], v[130:131] op_sel:[1,0,0] op_sel_hi:[1,1,1]
	v_pk_fma_f32 v[132:133], v[180:181], v[12:13], v[132:133] op_sel:[1,0,0] op_sel_hi:[1,1,1]
	v_pk_fma_f32 v[118:119], v[140:141], v[14:15], v[118:119] op_sel:[1,0,0] op_sel_hi:[1,1,1]
	v_pk_fma_f32 v[120:121], v[140:141], v[16:17], v[120:121] op_sel:[1,0,0] op_sel_hi:[1,1,1]
	v_pk_fma_f32 v[122:123], v[148:149], v[14:15], v[122:123] op_sel:[1,0,0] op_sel_hi:[1,1,1]
	v_pk_fma_f32 v[124:125], v[148:149], v[16:17], v[124:125] op_sel:[1,0,0] op_sel_hi:[1,1,1]
	v_pk_fma_f32 v[126:127], v[154:155], v[14:15], v[126:127] op_sel:[0,0,0] op_sel_hi:[0,1,1]
	v_pk_fma_f32 v[128:129], v[154:155], v[16:17], v[128:129] op_sel:[0,0,0] op_sel_hi:[0,1,1]
	v_pk_fma_f32 v[130:131], v[0:1], v[14:15], v[130:131] op_sel:[0,0,0] op_sel_hi:[0,1,1]
	v_pk_fma_f32 v[132:133], v[0:1], v[16:17], v[132:133] op_sel:[0,0,0] op_sel_hi:[0,1,1]
	s_add_i32 s0, s8, 0x1000
	buffer_load_dwordx4 v[34:37], v161, s[12:15], s0 offen nt
	buffer_load_dwordx4 v[2:5], v161, s[4:7], s0 offen nt
	s_add_i32 s0, s3, 64
	buffer_load_dword v168, v162, s[16:19], s0 offen
	s_add_i32 s0, s8, 0x1400
	buffer_load_dwordx4 v[42:45], v161, s[12:15], s0 offen nt
	buffer_load_dwordx4 v[6:9], v161, s[4:7], s0 offen nt
	s_add_i32 s0, s3, 0x50
	buffer_load_dword v164, v162, s[16:19], s0 offen
	s_add_i32 s0, s8, 0x1800
	buffer_load_dwordx4 v[38:41], v161, s[12:15], s0 offen nt
	buffer_load_dwordx4 v[10:13], v161, s[4:7], s0 offen nt
	s_add_i32 s0, s3, 0x60
	buffer_load_dword v165, v162, s[16:19], s0 offen
	s_add_i32 s0, s8, 0x1c00
	buffer_load_dwordx4 v[46:49], v161, s[12:15], s0 offen nt
	buffer_load_dwordx4 v[14:17], v161, s[4:7], s0 offen nt
	s_add_i32 s0, s3, 0x70
	buffer_load_dword v166, v162, s[16:19], s0 offen
	s_waitcnt vmcnt(24)
	v_pk_mul_f32 v[98:99], v[116:117], v[84:85]
	v_pk_mul_f32 v[100:101], v[116:117], v[88:89]
	v_pk_mul_f32 v[174:175], v[116:117], v[92:93]
	v_pk_mul_f32 v[176:177], v[116:117], v[96:97]
	v_pk_fma_f32 v[98:99], v[114:115], v[82:83], v[98:99]
	v_pk_fma_f32 v[100:101], v[114:115], v[86:87], v[100:101]
	v_pk_fma_f32 v[174:175], v[114:115], v[90:91], v[174:175]
	v_pk_fma_f32 v[176:177], v[114:115], v[94:95], v[176:177]
	v_add_f32_e32 v136, v98, v99
	v_add_f32_e32 v137, v100, v101
	v_add_f32_e32 v138, v174, v175
	v_add_f32_e32 v139, v176, v177
	v_pk_mul_f32 v[98:99], v[112:113], v[84:85]
	v_pk_mul_f32 v[100:101], v[112:113], v[88:89]
	v_pk_mul_f32 v[174:175], v[112:113], v[92:93]
	v_pk_mul_f32 v[176:177], v[112:113], v[96:97]
	v_pk_fma_f32 v[98:99], v[110:111], v[82:83], v[98:99]
	v_pk_fma_f32 v[100:101], v[110:111], v[86:87], v[100:101]
	v_pk_fma_f32 v[174:175], v[110:111], v[90:91], v[174:175]
	v_pk_fma_f32 v[176:177], v[110:111], v[94:95], v[176:177]
	v_add_f32_e32 v140, v98, v99
	v_add_f32_e32 v141, v100, v101
	v_add_f32_e32 v142, v174, v175
	v_add_f32_e32 v144, v176, v177
	v_pk_mul_f32 v[98:99], v[108:109], v[84:85]
	v_pk_mul_f32 v[100:101], v[108:109], v[88:89]
	v_pk_mul_f32 v[174:175], v[108:109], v[92:93]
	v_pk_mul_f32 v[176:177], v[108:109], v[96:97]
	v_pk_fma_f32 v[98:99], v[106:107], v[82:83], v[98:99]
	v_pk_fma_f32 v[100:101], v[106:107], v[86:87], v[100:101]
	v_pk_fma_f32 v[174:175], v[106:107], v[90:91], v[174:175]
	v_pk_fma_f32 v[176:177], v[106:107], v[94:95], v[176:177]
	v_add_f32_e32 v147, v98, v99
	v_add_f32_e32 v148, v100, v101
	v_add_f32_e32 v149, v174, v175
	v_add_f32_e32 v150, v176, v177
	v_pk_mul_f32 v[98:99], v[104:105], v[84:85]
	v_pk_mul_f32 v[100:101], v[104:105], v[88:89]
	v_pk_mul_f32 v[174:175], v[104:105], v[92:93]
	v_pk_mul_f32 v[176:177], v[104:105], v[96:97]
	v_pk_fma_f32 v[98:99], v[102:103], v[82:83], v[98:99]
	v_pk_fma_f32 v[100:101], v[102:103], v[86:87], v[100:101]
	v_pk_fma_f32 v[174:175], v[102:103], v[90:91], v[174:175]
	v_pk_fma_f32 v[176:177], v[102:103], v[94:95], v[176:177]
	v_add_f32_e32 v151, v98, v99
	v_add_f32_e32 v152, v100, v101
	v_add_f32_e32 v153, v174, v175
	v_add_f32_e32 v154, v176, v177
	v_add_f32_e32 v155, v146, v172
	v_add_f32_e32 v156, v155, v145
	v_add_f32_e32 v157, v156, v143
	v_add_f32_dpp v136, v136, v136 row_mirror row_mask:0xf bank_mask:0x3 bound_ctrl:1
	v_add_f32_dpp v137, v137, v137 row_mirror row_mask:0xf bank_mask:0x3 bound_ctrl:1
	v_add_f32_dpp v138, v138, v138 row_mirror row_mask:0xf bank_mask:0x3 bound_ctrl:1
	v_add_f32_dpp v139, v139, v139 row_mirror row_mask:0xf bank_mask:0x3 bound_ctrl:1
	v_add_f32_dpp v140, v140, v140 row_mirror row_mask:0xf bank_mask:0x3 bound_ctrl:1
	v_add_f32_dpp v141, v141, v141 row_mirror row_mask:0xf bank_mask:0x3 bound_ctrl:1
	v_add_f32_dpp v142, v142, v142 row_mirror row_mask:0xf bank_mask:0x3 bound_ctrl:1
	v_add_f32_dpp v144, v144, v144 row_mirror row_mask:0xf bank_mask:0x3 bound_ctrl:1
	v_add_f32_dpp v136, v147, v147 row_mirror row_mask:0xf bank_mask:0xc bound_ctrl:1
	v_add_f32_dpp v137, v148, v148 row_mirror row_mask:0xf bank_mask:0xc bound_ctrl:1
	v_add_f32_dpp v138, v149, v149 row_mirror row_mask:0xf bank_mask:0xc bound_ctrl:1
	v_add_f32_dpp v139, v150, v150 row_mirror row_mask:0xf bank_mask:0xc bound_ctrl:1
	v_add_f32_dpp v140, v151, v151 row_mirror row_mask:0xf bank_mask:0xc bound_ctrl:1
	v_add_f32_dpp v141, v152, v152 row_mirror row_mask:0xf bank_mask:0xc bound_ctrl:1
	v_add_f32_dpp v142, v153, v153 row_mirror row_mask:0xf bank_mask:0xc bound_ctrl:1
	v_add_f32_dpp v144, v154, v154 row_mirror row_mask:0xf bank_mask:0xc bound_ctrl:1
	v_add_f32_dpp v136, v136, v136 row_half_mirror row_mask:0xf bank_mask:0x5 bound_ctrl:1
	v_add_f32_dpp v137, v137, v137 row_half_mirror row_mask:0xf bank_mask:0x5 bound_ctrl:1
	v_add_f32_dpp v138, v138, v138 row_half_mirror row_mask:0xf bank_mask:0x5 bound_ctrl:1
	v_add_f32_dpp v139, v139, v139 row_half_mirror row_mask:0xf bank_mask:0x5 bound_ctrl:1
	v_add_f32_dpp v136, v140, v140 row_half_mirror row_mask:0xf bank_mask:0xa bound_ctrl:1
	v_add_f32_dpp v137, v141, v141 row_half_mirror row_mask:0xf bank_mask:0xa bound_ctrl:1
	v_add_f32_dpp v138, v142, v142 row_half_mirror row_mask:0xf bank_mask:0xa bound_ctrl:1
	v_add_f32_dpp v139, v144, v144 row_half_mirror row_mask:0xf bank_mask:0xa bound_ctrl:1
	v_add_f32_dpp v136, v136, v136 quad_perm:[2,3,0,1] row_mask:0xf bank_mask:0xf bound_ctrl:1
	v_add_f32_dpp v138, v138, v138 quad_perm:[2,3,0,1] row_mask:0xf bank_mask:0xf bound_ctrl:1
	v_add_f32_dpp v137, v137, v137 quad_perm:[2,3,0,1] row_mask:0xf bank_mask:0xf bound_ctrl:1
	v_add_f32_dpp v139, v139, v139 quad_perm:[2,3,0,1] row_mask:0xf bank_mask:0xf bound_ctrl:1
	v_cndmask_b32_e64 v173, v155, v146, s[28:29]
	v_cndmask_b32_e64 v178, v157, v156, s[28:29]
	v_cndmask_b32_e64 v136, v136, v138, s[24:25]
	v_cndmask_b32_e64 v137, v137, v139, s[24:25]
	v_cndmask_b32_e64 v173, v178, v173, s[24:25]
	v_add_f32_e32 v146, v157, v163
	v_add_f32_dpp v136, v136, v136 quad_perm:[1,0,3,2] row_mask:0xf bank_mask:0xf bound_ctrl:1
	v_add_f32_dpp v137, v137, v137 quad_perm:[1,0,3,2] row_mask:0xf bank_mask:0xf bound_ctrl:1
	v_cndmask_b32_e64 v136, v136, v137, s[28:29]
	v_fmac_f32_e32 v136, 0x3fb8aa3b, v173
	s_nop 1
	v_max_f32_dpp v179, v136, v136 quad_perm:[1,0,3,2] row_mask:0xf bank_mask:0xf bound_ctrl:1
	s_nop 1
	v_max_f32_dpp v180, v179, v179 quad_perm:[2,3,0,1] row_mask:0xf bank_mask:0xf bound_ctrl:1
	v_max_f32_e32 v180, v134, v180
	v_sub_f32_e32 v155, v134, v180
	v_sub_f32_e32 v156, v136, v180
	v_mov_b32_e32 v134, v180
	v_exp_f32_e32 v155, v155
	v_exp_f32_e32 v156, v156
	s_nop 0
	v_mov_b32_dpp v137, v155 row_newbcast:0 row_mask:0xf bank_mask:0xf
	v_mov_b32_dpp v142, v155 row_newbcast:4 row_mask:0xf bank_mask:0xf
	v_mov_b32_dpp v150, v155 row_newbcast:8 row_mask:0xf bank_mask:0xf
	v_mov_b32_dpp v178, v155 row_newbcast:12 row_mask:0xf bank_mask:0xf
	v_add_f32_dpp v157, v156, v156 quad_perm:[1,0,3,2] row_mask:0xf bank_mask:0xf bound_ctrl:1
	v_mov_b32_dpp v138, v156 row_newbcast:0 row_mask:0xf bank_mask:0xf
	v_mov_b32_dpp v139, v156 row_newbcast:1 row_mask:0xf bank_mask:0xf
	v_mov_b32_dpp v140, v156 row_newbcast:2 row_mask:0xf bank_mask:0xf
	v_mov_b32_dpp v141, v156 row_newbcast:3 row_mask:0xf bank_mask:0xf
	v_add_f32_dpp v173, v157, v157 quad_perm:[2,3,0,1] row_mask:0xf bank_mask:0xf bound_ctrl:1
	v_mov_b32_dpp v144, v156 row_newbcast:4 row_mask:0xf bank_mask:0xf
	v_mov_b32_dpp v147, v156 row_newbcast:5 row_mask:0xf bank_mask:0xf
	v_mov_b32_dpp v148, v156 row_newbcast:6 row_mask:0xf bank_mask:0xf
	v_mov_b32_dpp v149, v156 row_newbcast:7 row_mask:0xf bank_mask:0xf
	v_fma_f32 v135, v135, v155, v173
	v_mov_b32_dpp v151, v156 row_newbcast:8 row_mask:0xf bank_mask:0xf
	v_mov_b32_dpp v152, v156 row_newbcast:9 row_mask:0xf bank_mask:0xf
	v_mov_b32_dpp v153, v156 row_newbcast:10 row_mask:0xf bank_mask:0xf
	v_mov_b32_dpp v154, v156 row_newbcast:11 row_mask:0xf bank_mask:0xf
	v_mov_b32_dpp v179, v156 row_newbcast:12 row_mask:0xf bank_mask:0xf
	v_mov_b32_dpp v180, v156 row_newbcast:13 row_mask:0xf bank_mask:0xf
	v_mov_b32_dpp v181, v156 row_newbcast:14 row_mask:0xf bank_mask:0xf
	v_mov_b32_dpp v0, v156 row_newbcast:15 row_mask:0xf bank_mask:0xf
	v_pk_mul_f32 v[118:119], v[118:119], v[136:137] op_sel:[0,1] op_sel_hi:[1,1]
	v_pk_mul_f32 v[120:121], v[120:121], v[136:137] op_sel:[0,1] op_sel_hi:[1,1]
	v_pk_mul_f32 v[122:123], v[122:123], v[142:143] op_sel:[0,0] op_sel_hi:[1,0]
	v_pk_mul_f32 v[124:125], v[124:125], v[142:143] op_sel:[0,0] op_sel_hi:[1,0]
	v_pk_mul_f32 v[126:127], v[126:127], v[150:151] op_sel:[0,0] op_sel_hi:[1,0]
	v_pk_mul_f32 v[128:129], v[128:129], v[150:151] op_sel:[0,0] op_sel_hi:[1,0]
	v_pk_mul_f32 v[130:131], v[130:131], v[178:179] op_sel:[0,0] op_sel_hi:[1,0]
	v_pk_mul_f32 v[132:133], v[132:133], v[178:179] op_sel:[0,0] op_sel_hi:[1,0]
	v_pk_fma_f32 v[118:119], v[138:139], v[66:67], v[118:119] op_sel:[0,0,0] op_sel_hi:[0,1,1]
	v_pk_fma_f32 v[120:121], v[138:139], v[68:69], v[120:121] op_sel:[0,0,0] op_sel_hi:[0,1,1]
	v_pk_fma_f32 v[122:123], v[144:145], v[66:67], v[122:123] op_sel:[0,0,0] op_sel_hi:[0,1,1]
	v_pk_fma_f32 v[124:125], v[144:145], v[68:69], v[124:125] op_sel:[0,0,0] op_sel_hi:[0,1,1]
	v_pk_fma_f32 v[126:127], v[150:151], v[66:67], v[126:127] op_sel:[1,0,0] op_sel_hi:[1,1,1]
	v_pk_fma_f32 v[128:129], v[150:151], v[68:69], v[128:129] op_sel:[1,0,0] op_sel_hi:[1,1,1]
	v_pk_fma_f32 v[130:131], v[178:179], v[66:67], v[130:131] op_sel:[1,0,0] op_sel_hi:[1,1,1]
	v_pk_fma_f32 v[132:133], v[178:179], v[68:69], v[132:133] op_sel:[1,0,0] op_sel_hi:[1,1,1]
	v_pk_fma_f32 v[118:119], v[138:139], v[70:71], v[118:119] op_sel:[1,0,0] op_sel_hi:[1,1,1]
	v_pk_fma_f32 v[120:121], v[138:139], v[72:73], v[120:121] op_sel:[1,0,0] op_sel_hi:[1,1,1]
	v_pk_fma_f32 v[122:123], v[146:147], v[70:71], v[122:123] op_sel:[1,0,0] op_sel_hi:[1,1,1]
	v_pk_fma_f32 v[124:125], v[146:147], v[72:73], v[124:125] op_sel:[1,0,0] op_sel_hi:[1,1,1]
	v_pk_fma_f32 v[126:127], v[152:153], v[70:71], v[126:127] op_sel:[0,0,0] op_sel_hi:[0,1,1]
	v_pk_fma_f32 v[128:129], v[152:153], v[72:73], v[128:129] op_sel:[0,0,0] op_sel_hi:[0,1,1]
	v_pk_fma_f32 v[130:131], v[180:181], v[70:71], v[130:131] op_sel:[0,0,0] op_sel_hi:[0,1,1]
	v_pk_fma_f32 v[132:133], v[180:181], v[72:73], v[132:133] op_sel:[0,0,0] op_sel_hi:[0,1,1]
	v_pk_fma_f32 v[118:119], v[140:141], v[74:75], v[118:119] op_sel:[0,0,0] op_sel_hi:[0,1,1]
	v_pk_fma_f32 v[120:121], v[140:141], v[76:77], v[120:121] op_sel:[0,0,0] op_sel_hi:[0,1,1]
	v_pk_fma_f32 v[122:123], v[148:149], v[74:75], v[122:123] op_sel:[0,0,0] op_sel_hi:[0,1,1]
	v_pk_fma_f32 v[124:125], v[148:149], v[76:77], v[124:125] op_sel:[0,0,0] op_sel_hi:[0,1,1]
	v_pk_fma_f32 v[126:127], v[152:153], v[74:75], v[126:127] op_sel:[1,0,0] op_sel_hi:[1,1,1]
	v_pk_fma_f32 v[128:129], v[152:153], v[76:77], v[128:129] op_sel:[1,0,0] op_sel_hi:[1,1,1]
	v_pk_fma_f32 v[130:131], v[180:181], v[74:75], v[130:131] op_sel:[1,0,0] op_sel_hi:[1,1,1]
	v_pk_fma_f32 v[132:133], v[180:181], v[76:77], v[132:133] op_sel:[1,0,0] op_sel_hi:[1,1,1]
	v_pk_fma_f32 v[118:119], v[140:141], v[78:79], v[118:119] op_sel:[1,0,0] op_sel_hi:[1,1,1]
	v_pk_fma_f32 v[120:121], v[140:141], v[80:81], v[120:121] op_sel:[1,0,0] op_sel_hi:[1,1,1]
	v_pk_fma_f32 v[122:123], v[148:149], v[78:79], v[122:123] op_sel:[1,0,0] op_sel_hi:[1,1,1]
	v_pk_fma_f32 v[124:125], v[148:149], v[80:81], v[124:125] op_sel:[1,0,0] op_sel_hi:[1,1,1]
	v_pk_fma_f32 v[126:127], v[154:155], v[78:79], v[126:127] op_sel:[0,0,0] op_sel_hi:[0,1,1]
	v_pk_fma_f32 v[128:129], v[154:155], v[80:81], v[128:129] op_sel:[0,0,0] op_sel_hi:[0,1,1]
	v_pk_fma_f32 v[130:131], v[0:1], v[78:79], v[130:131] op_sel:[0,0,0] op_sel_hi:[0,1,1]
	v_pk_fma_f32 v[132:133], v[0:1], v[80:81], v[132:133] op_sel:[0,0,0] op_sel_hi:[0,1,1]
	s_add_i32 s0, s8, 0x400
	buffer_load_dwordx4 v[82:85], v161, s[12:15], s8 offen nt
	buffer_load_dwordx4 v[66:69], v161, s[4:7], s8 offen nt
	buffer_load_dword v163, v162, s[16:19], s3 offen
	buffer_load_dwordx4 v[86:89], v161, s[12:15], s0 offen nt
	buffer_load_dwordx4 v[70:73], v161, s[4:7], s0 offen nt
	s_add_i32 s0, s3, 16
	buffer_load_dword v143, v162, s[16:19], s0 offen
	s_add_i32 s0, s8, 0x800
	buffer_load_dwordx4 v[90:93], v161, s[12:15], s0 offen nt
	buffer_load_dwordx4 v[74:77], v161, s[4:7], s0 offen nt
	s_add_i32 s0, s3, 32
	buffer_load_dword v145, v162, s[16:19], s0 offen
	s_add_i32 s0, s8, 0xc00
	buffer_load_dwordx4 v[94:97], v161, s[12:15], s0 offen nt
	buffer_load_dwordx4 v[78:81], v161, s[4:7], s0 offen nt
	s_add_i32 s0, s3, 48
	buffer_load_dword v172, v162, s[16:19], s0 offen
	s_add_i32 s2, s2, -12
	s_addk_i32 s3, 0xff40
	s_addk_i32 s8, 0xd000
	s_cmp_lt_u32 s2, 24
	s_cbranch_scc0 .Lpg_loop
	s_waitcnt vmcnt(24)
	v_pk_mul_f32 v[98:99], v[116:117], v[52:53]
	v_pk_mul_f32 v[100:101], v[116:117], v[60:61]
	v_pk_mul_f32 v[174:175], v[116:117], v[56:57]
	v_pk_mul_f32 v[176:177], v[116:117], v[64:65]
	v_pk_fma_f32 v[98:99], v[114:115], v[50:51], v[98:99]
	v_pk_fma_f32 v[100:101], v[114:115], v[58:59], v[100:101]
	v_pk_fma_f32 v[174:175], v[114:115], v[54:55], v[174:175]
	v_pk_fma_f32 v[176:177], v[114:115], v[62:63], v[176:177]
	v_add_f32_e32 v136, v98, v99
	v_add_f32_e32 v137, v100, v101
	v_add_f32_e32 v138, v174, v175
	v_add_f32_e32 v139, v176, v177
	v_pk_mul_f32 v[98:99], v[112:113], v[52:53]
	v_pk_mul_f32 v[100:101], v[112:113], v[60:61]
	v_pk_mul_f32 v[174:175], v[112:113], v[56:57]
	v_pk_mul_f32 v[176:177], v[112:113], v[64:65]
	v_pk_fma_f32 v[98:99], v[110:111], v[50:51], v[98:99]
	v_pk_fma_f32 v[100:101], v[110:111], v[58:59], v[100:101]
	v_pk_fma_f32 v[174:175], v[110:111], v[54:55], v[174:175]
	v_pk_fma_f32 v[176:177], v[110:111], v[62:63], v[176:177]
	v_add_f32_e32 v140, v98, v99
	v_add_f32_e32 v141, v100, v101
	v_add_f32_e32 v142, v174, v175
	v_add_f32_e32 v144, v176, v177
	v_pk_mul_f32 v[98:99], v[108:109], v[52:53]
	v_pk_mul_f32 v[100:101], v[108:109], v[60:61]
	v_pk_mul_f32 v[174:175], v[108:109], v[56:57]
	v_pk_mul_f32 v[176:177], v[108:109], v[64:65]
	v_pk_fma_f32 v[98:99], v[106:107], v[50:51], v[98:99]
	v_pk_fma_f32 v[100:101], v[106:107], v[58:59], v[100:101]
	v_pk_fma_f32 v[174:175], v[106:107], v[54:55], v[174:175]
	v_pk_fma_f32 v[176:177], v[106:107], v[62:63], v[176:177]
	v_add_f32_e32 v147, v98, v99
	v_add_f32_e32 v148, v100, v101
	v_add_f32_e32 v149, v174, v175
	v_add_f32_e32 v150, v176, v177
	v_pk_mul_f32 v[98:99], v[104:105], v[52:53]
	v_pk_mul_f32 v[100:101], v[104:105], v[60:61]
	v_pk_mul_f32 v[174:175], v[104:105], v[56:57]
	v_pk_mul_f32 v[176:177], v[104:105], v[64:65]
	v_pk_fma_f32 v[98:99], v[102:103], v[50:51], v[98:99]
	v_pk_fma_f32 v[100:101], v[102:103], v[58:59], v[100:101]
	v_pk_fma_f32 v[174:175], v[102:103], v[54:55], v[174:175]
	v_pk_fma_f32 v[176:177], v[102:103], v[62:63], v[176:177]
	v_add_f32_e32 v151, v98, v99
	v_add_f32_e32 v152, v100, v101
	v_add_f32_e32 v153, v174, v175
	v_add_f32_e32 v154, v176, v177
	v_add_f32_e32 v155, v146, v171
	v_add_f32_e32 v156, v155, v170
	v_add_f32_e32 v157, v156, v169
	v_add_f32_dpp v136, v136, v136 row_mirror row_mask:0xf bank_mask:0x3 bound_ctrl:1
	v_add_f32_dpp v137, v137, v137 row_mirror row_mask:0xf bank_mask:0x3 bound_ctrl:1
	v_add_f32_dpp v138, v138, v138 row_mirror row_mask:0xf bank_mask:0x3 bound_ctrl:1
	v_add_f32_dpp v139, v139, v139 row_mirror row_mask:0xf bank_mask:0x3 bound_ctrl:1
	v_add_f32_dpp v140, v140, v140 row_mirror row_mask:0xf bank_mask:0x3 bound_ctrl:1
	v_add_f32_dpp v141, v141, v141 row_mirror row_mask:0xf bank_mask:0x3 bound_ctrl:1
	v_add_f32_dpp v142, v142, v142 row_mirror row_mask:0xf bank_mask:0x3 bound_ctrl:1
	v_add_f32_dpp v144, v144, v144 row_mirror row_mask:0xf bank_mask:0x3 bound_ctrl:1
	v_add_f32_dpp v136, v147, v147 row_mirror row_mask:0xf bank_mask:0xc bound_ctrl:1
	v_add_f32_dpp v137, v148, v148 row_mirror row_mask:0xf bank_mask:0xc bound_ctrl:1
	v_add_f32_dpp v138, v149, v149 row_mirror row_mask:0xf bank_mask:0xc bound_ctrl:1
	v_add_f32_dpp v139, v150, v150 row_mirror row_mask:0xf bank_mask:0xc bound_ctrl:1
	v_add_f32_dpp v140, v151, v151 row_mirror row_mask:0xf bank_mask:0xc bound_ctrl:1
	v_add_f32_dpp v141, v152, v152 row_mirror row_mask:0xf bank_mask:0xc bound_ctrl:1
	v_add_f32_dpp v142, v153, v153 row_mirror row_mask:0xf bank_mask:0xc bound_ctrl:1
	v_add_f32_dpp v144, v154, v154 row_mirror row_mask:0xf bank_mask:0xc bound_ctrl:1
	v_add_f32_dpp v136, v136, v136 row_half_mirror row_mask:0xf bank_mask:0x5 bound_ctrl:1
	v_add_f32_dpp v137, v137, v137 row_half_mirror row_mask:0xf bank_mask:0x5 bound_ctrl:1
	v_add_f32_dpp v138, v138, v138 row_half_mirror row_mask:0xf bank_mask:0x5 bound_ctrl:1
	v_add_f32_dpp v139, v139, v139 row_half_mirror row_mask:0xf bank_mask:0x5 bound_ctrl:1
	v_add_f32_dpp v136, v140, v140 row_half_mirror row_mask:0xf bank_mask:0xa bound_ctrl:1
	v_add_f32_dpp v137, v141, v141 row_half_mirror row_mask:0xf bank_mask:0xa bound_ctrl:1
	v_add_f32_dpp v138, v142, v142 row_half_mirror row_mask:0xf bank_mask:0xa bound_ctrl:1
	v_add_f32_dpp v139, v144, v144 row_half_mirror row_mask:0xf bank_mask:0xa bound_ctrl:1
	v_add_f32_dpp v136, v136, v136 quad_perm:[2,3,0,1] row_mask:0xf bank_mask:0xf bound_ctrl:1
	v_add_f32_dpp v138, v138, v138 quad_perm:[2,3,0,1] row_mask:0xf bank_mask:0xf bound_ctrl:1
	v_add_f32_dpp v137, v137, v137 quad_perm:[2,3,0,1] row_mask:0xf bank_mask:0xf bound_ctrl:1
	v_add_f32_dpp v139, v139, v139 quad_perm:[2,3,0,1] row_mask:0xf bank_mask:0xf bound_ctrl:1
	v_cndmask_b32_e64 v173, v155, v146, s[28:29]
	v_cndmask_b32_e64 v178, v157, v156, s[28:29]
	v_cndmask_b32_e64 v136, v136, v138, s[24:25]
	v_cndmask_b32_e64 v137, v137, v139, s[24:25]
	v_cndmask_b32_e64 v173, v178, v173, s[24:25]
	v_add_f32_e32 v146, v157, v167
	v_add_f32_dpp v136, v136, v136 quad_perm:[1,0,3,2] row_mask:0xf bank_mask:0xf bound_ctrl:1
	v_add_f32_dpp v137, v137, v137 quad_perm:[1,0,3,2] row_mask:0xf bank_mask:0xf bound_ctrl:1
	v_cndmask_b32_e64 v136, v136, v137, s[28:29]
	v_fmac_f32_e32 v136, 0x3fb8aa3b, v173
	s_nop 1
	v_max_f32_dpp v179, v136, v136 quad_perm:[1,0,3,2] row_mask:0xf bank_mask:0xf bound_ctrl:1
	s_nop 1
	v_max_f32_dpp v180, v179, v179 quad_perm:[2,3,0,1] row_mask:0xf bank_mask:0xf bound_ctrl:1
	v_max_f32_e32 v180, v134, v180
	v_sub_f32_e32 v155, v134, v180
	v_sub_f32_e32 v156, v136, v180
	v_mov_b32_e32 v134, v180
	v_exp_f32_e32 v155, v155
	v_exp_f32_e32 v156, v156
	s_nop 0
	v_mov_b32_dpp v137, v155 row_newbcast:0 row_mask:0xf bank_mask:0xf
	v_mov_b32_dpp v142, v155 row_newbcast:4 row_mask:0xf bank_mask:0xf
	v_mov_b32_dpp v150, v155 row_newbcast:8 row_mask:0xf bank_mask:0xf
	v_mov_b32_dpp v178, v155 row_newbcast:12 row_mask:0xf bank_mask:0xf
	v_add_f32_dpp v157, v156, v156 quad_perm:[1,0,3,2] row_mask:0xf bank_mask:0xf bound_ctrl:1
	v_mov_b32_dpp v138, v156 row_newbcast:0 row_mask:0xf bank_mask:0xf
	v_mov_b32_dpp v139, v156 row_newbcast:1 row_mask:0xf bank_mask:0xf
	v_mov_b32_dpp v140, v156 row_newbcast:2 row_mask:0xf bank_mask:0xf
	v_mov_b32_dpp v141, v156 row_newbcast:3 row_mask:0xf bank_mask:0xf
	v_add_f32_dpp v173, v157, v157 quad_perm:[2,3,0,1] row_mask:0xf bank_mask:0xf bound_ctrl:1
	v_mov_b32_dpp v144, v156 row_newbcast:4 row_mask:0xf bank_mask:0xf
	v_mov_b32_dpp v147, v156 row_newbcast:5 row_mask:0xf bank_mask:0xf
	v_mov_b32_dpp v148, v156 row_newbcast:6 row_mask:0xf bank_mask:0xf
	v_mov_b32_dpp v149, v156 row_newbcast:7 row_mask:0xf bank_mask:0xf
	v_fma_f32 v135, v135, v155, v173
	v_mov_b32_dpp v151, v156 row_newbcast:8 row_mask:0xf bank_mask:0xf
	v_mov_b32_dpp v152, v156 row_newbcast:9 row_mask:0xf bank_mask:0xf
	v_mov_b32_dpp v153, v156 row_newbcast:10 row_mask:0xf bank_mask:0xf
	v_mov_b32_dpp v154, v156 row_newbcast:11 row_mask:0xf bank_mask:0xf
	v_mov_b32_dpp v179, v156 row_newbcast:12 row_mask:0xf bank_mask:0xf
	v_mov_b32_dpp v180, v156 row_newbcast:13 row_mask:0xf bank_mask:0xf
	v_mov_b32_dpp v181, v156 row_newbcast:14 row_mask:0xf bank_mask:0xf
	v_mov_b32_dpp v0, v156 row_newbcast:15 row_mask:0xf bank_mask:0xf
	v_pk_mul_f32 v[118:119], v[118:119], v[136:137] op_sel:[0,1] op_sel_hi:[1,1]
	v_pk_mul_f32 v[120:121], v[120:121], v[136:137] op_sel:[0,1] op_sel_hi:[1,1]
	v_pk_mul_f32 v[122:123], v[122:123], v[142:143] op_sel:[0,0] op_sel_hi:[1,0]
	v_pk_mul_f32 v[124:125], v[124:125], v[142:143] op_sel:[0,0] op_sel_hi:[1,0]
	v_pk_mul_f32 v[126:127], v[126:127], v[150:151] op_sel:[0,0] op_sel_hi:[1,0]
	v_pk_mul_f32 v[128:129], v[128:129], v[150:151] op_sel:[0,0] op_sel_hi:[1,0]
	v_pk_mul_f32 v[130:131], v[130:131], v[178:179] op_sel:[0,0] op_sel_hi:[1,0]
	v_pk_mul_f32 v[132:133], v[132:133], v[178:179] op_sel:[0,0] op_sel_hi:[1,0]
	v_pk_fma_f32 v[118:119], v[138:139], v[22:23], v[118:119] op_sel:[0,0,0] op_sel_hi:[0,1,1]
	v_pk_fma_f32 v[120:121], v[138:139], v[24:25], v[120:121] op_sel:[0,0,0] op_sel_hi:[0,1,1]
	v_pk_fma_f32 v[122:123], v[144:145], v[22:23], v[122:123] op_sel:[0,0,0] op_sel_hi:[0,1,1]
	v_pk_fma_f32 v[124:125], v[144:145], v[24:25], v[124:125] op_sel:[0,0,0] op_sel_hi:[0,1,1]
	v_pk_fma_f32 v[126:127], v[150:151], v[22:23], v[126:127] op_sel:[1,0,0] op_sel_hi:[1,1,1]
	v_pk_fma_f32 v[128:129], v[150:151], v[24:25], v[128:129] op_sel:[1,0,0] op_sel_hi:[1,1,1]
	v_pk_fma_f32 v[130:131], v[178:179], v[22:23], v[130:131] op_sel:[1,0,0] op_sel_hi:[1,1,1]
	v_pk_fma_f32 v[132:133], v[178:179], v[24:25], v[132:133] op_sel:[1,0,0] op_sel_hi:[1,1,1]
	v_pk_fma_f32 v[118:119], v[138:139], v[18:19], v[118:119] op_sel:[1,0,0] op_sel_hi:[1,1,1]
	v_pk_fma_f32 v[120:121], v[138:139], v[20:21], v[120:121] op_sel:[1,0,0] op_sel_hi:[1,1,1]
	v_pk_fma_f32 v[122:123], v[146:147], v[18:19], v[122:123] op_sel:[1,0,0] op_sel_hi:[1,1,1]
	v_pk_fma_f32 v[124:125], v[146:147], v[20:21], v[124:125] op_sel:[1,0,0] op_sel_hi:[1,1,1]
	v_pk_fma_f32 v[126:127], v[152:153], v[18:19], v[126:127] op_sel:[0,0,0] op_sel_hi:[0,1,1]
	v_pk_fma_f32 v[128:129], v[152:153], v[20:21], v[128:129] op_sel:[0,0,0] op_sel_hi:[0,1,1]
	v_pk_fma_f32 v[130:131], v[180:181], v[18:19], v[130:131] op_sel:[0,0,0] op_sel_hi:[0,1,1]
	v_pk_fma_f32 v[132:133], v[180:181], v[20:21], v[132:133] op_sel:[0,0,0] op_sel_hi:[0,1,1]
	v_pk_fma_f32 v[118:119], v[140:141], v[26:27], v[118:119] op_sel:[0,0,0] op_sel_hi:[0,1,1]
	v_pk_fma_f32 v[120:121], v[140:141], v[28:29], v[120:121] op_sel:[0,0,0] op_sel_hi:[0,1,1]
	v_pk_fma_f32 v[122:123], v[148:149], v[26:27], v[122:123] op_sel:[0,0,0] op_sel_hi:[0,1,1]
	v_pk_fma_f32 v[124:125], v[148:149], v[28:29], v[124:125] op_sel:[0,0,0] op_sel_hi:[0,1,1]
	v_pk_fma_f32 v[126:127], v[152:153], v[26:27], v[126:127] op_sel:[1,0,0] op_sel_hi:[1,1,1]
	v_pk_fma_f32 v[128:129], v[152:153], v[28:29], v[128:129] op_sel:[1,0,0] op_sel_hi:[1,1,1]
	v_pk_fma_f32 v[130:131], v[180:181], v[26:27], v[130:131] op_sel:[1,0,0] op_sel_hi:[1,1,1]
	v_pk_fma_f32 v[132:133], v[180:181], v[28:29], v[132:133] op_sel:[1,0,0] op_sel_hi:[1,1,1]
	v_pk_fma_f32 v[118:119], v[140:141], v[30:31], v[118:119] op_sel:[1,0,0] op_sel_hi:[1,1,1]
	v_pk_fma_f32 v[120:121], v[140:141], v[32:33], v[120:121] op_sel:[1,0,0] op_sel_hi:[1,1,1]
	v_pk_fma_f32 v[122:123], v[148:149], v[30:31], v[122:123] op_sel:[1,0,0] op_sel_hi:[1,1,1]
	v_pk_fma_f32 v[124:125], v[148:149], v[32:33], v[124:125] op_sel:[1,0,0] op_sel_hi:[1,1,1]
	v_pk_fma_f32 v[126:127], v[154:155], v[30:31], v[126:127] op_sel:[0,0,0] op_sel_hi:[0,1,1]
	v_pk_fma_f32 v[128:129], v[154:155], v[32:33], v[128:129] op_sel:[0,0,0] op_sel_hi:[0,1,1]
	v_pk_fma_f32 v[130:131], v[0:1], v[30:31], v[130:131] op_sel:[0,0,0] op_sel_hi:[0,1,1]
	v_pk_fma_f32 v[132:133], v[0:1], v[32:33], v[132:133] op_sel:[0,0,0] op_sel_hi:[0,1,1]
	s_waitcnt vmcnt(12)
	v_pk_mul_f32 v[98:99], v[116:117], v[36:37]
	v_pk_mul_f32 v[100:101], v[116:117], v[44:45]
	v_pk_mul_f32 v[174:175], v[116:117], v[40:41]
	v_pk_mul_f32 v[176:177], v[116:117], v[48:49]
	v_pk_fma_f32 v[98:99], v[114:115], v[34:35], v[98:99]
	v_pk_fma_f32 v[100:101], v[114:115], v[42:43], v[100:101]
	v_pk_fma_f32 v[174:175], v[114:115], v[38:39], v[174:175]
	v_pk_fma_f32 v[176:177], v[114:115], v[46:47], v[176:177]
	v_add_f32_e32 v136, v98, v99
	v_add_f32_e32 v137, v100, v101
	v_add_f32_e32 v138, v174, v175
	v_add_f32_e32 v139, v176, v177
	v_pk_mul_f32 v[98:99], v[112:113], v[36:37]
	v_pk_mul_f32 v[100:101], v[112:113], v[44:45]
	v_pk_mul_f32 v[174:175], v[112:113], v[40:41]
	v_pk_mul_f32 v[176:177], v[112:113], v[48:49]
	v_pk_fma_f32 v[98:99], v[110:111], v[34:35], v[98:99]
	v_pk_fma_f32 v[100:101], v[110:111], v[42:43], v[100:101]
	v_pk_fma_f32 v[174:175], v[110:111], v[38:39], v[174:175]
	v_pk_fma_f32 v[176:177], v[110:111], v[46:47], v[176:177]
	v_add_f32_e32 v140, v98, v99
	v_add_f32_e32 v141, v100, v101
	v_add_f32_e32 v142, v174, v175
	v_add_f32_e32 v144, v176, v177
	v_pk_mul_f32 v[98:99], v[108:109], v[36:37]
	v_pk_mul_f32 v[100:101], v[108:109], v[44:45]
	v_pk_mul_f32 v[174:175], v[108:109], v[40:41]
	v_pk_mul_f32 v[176:177], v[108:109], v[48:49]
	v_pk_fma_f32 v[98:99], v[106:107], v[34:35], v[98:99]
	v_pk_fma_f32 v[100:101], v[106:107], v[42:43], v[100:101]
	v_pk_fma_f32 v[174:175], v[106:107], v[38:39], v[174:175]
	v_pk_fma_f32 v[176:177], v[106:107], v[46:47], v[176:177]
	v_add_f32_e32 v147, v98, v99
	v_add_f32_e32 v148, v100, v101
	v_add_f32_e32 v149, v174, v175
	v_add_f32_e32 v150, v176, v177
	v_pk_mul_f32 v[98:99], v[104:105], v[36:37]
	v_pk_mul_f32 v[100:101], v[104:105], v[44:45]
	v_pk_mul_f32 v[174:175], v[104:105], v[40:41]
	v_pk_mul_f32 v[176:177], v[104:105], v[48:49]
	v_pk_fma_f32 v[98:99], v[102:103], v[34:35], v[98:99]
	v_pk_fma_f32 v[100:101], v[102:103], v[42:43], v[100:101]
	v_pk_fma_f32 v[174:175], v[102:103], v[38:39], v[174:175]
	v_pk_fma_f32 v[176:177], v[102:103], v[46:47], v[176:177]
	v_add_f32_e32 v151, v98, v99
	v_add_f32_e32 v152, v100, v101
	v_add_f32_e32 v153, v174, v175
	v_add_f32_e32 v154, v176, v177
	v_add_f32_e32 v155, v146, v166
	v_add_f32_e32 v156, v155, v165
	v_add_f32_e32 v157, v156, v164
	v_add_f32_dpp v136, v136, v136 row_mirror row_mask:0xf bank_mask:0x3 bound_ctrl:1
	v_add_f32_dpp v137, v137, v137 row_mirror row_mask:0xf bank_mask:0x3 bound_ctrl:1
	v_add_f32_dpp v138, v138, v138 row_mirror row_mask:0xf bank_mask:0x3 bound_ctrl:1
	v_add_f32_dpp v139, v139, v139 row_mirror row_mask:0xf bank_mask:0x3 bound_ctrl:1
	v_add_f32_dpp v140, v140, v140 row_mirror row_mask:0xf bank_mask:0x3 bound_ctrl:1
	v_add_f32_dpp v141, v141, v141 row_mirror row_mask:0xf bank_mask:0x3 bound_ctrl:1
	v_add_f32_dpp v142, v142, v142 row_mirror row_mask:0xf bank_mask:0x3 bound_ctrl:1
	v_add_f32_dpp v144, v144, v144 row_mirror row_mask:0xf bank_mask:0x3 bound_ctrl:1
	v_add_f32_dpp v136, v147, v147 row_mirror row_mask:0xf bank_mask:0xc bound_ctrl:1
	v_add_f32_dpp v137, v148, v148 row_mirror row_mask:0xf bank_mask:0xc bound_ctrl:1
	v_add_f32_dpp v138, v149, v149 row_mirror row_mask:0xf bank_mask:0xc bound_ctrl:1
	v_add_f32_dpp v139, v150, v150 row_mirror row_mask:0xf bank_mask:0xc bound_ctrl:1
	v_add_f32_dpp v140, v151, v151 row_mirror row_mask:0xf bank_mask:0xc bound_ctrl:1
	v_add_f32_dpp v141, v152, v152 row_mirror row_mask:0xf bank_mask:0xc bound_ctrl:1
	v_add_f32_dpp v142, v153, v153 row_mirror row_mask:0xf bank_mask:0xc bound_ctrl:1
	v_add_f32_dpp v144, v154, v154 row_mirror row_mask:0xf bank_mask:0xc bound_ctrl:1
	v_add_f32_dpp v136, v136, v136 row_half_mirror row_mask:0xf bank_mask:0x5 bound_ctrl:1
	v_add_f32_dpp v137, v137, v137 row_half_mirror row_mask:0xf bank_mask:0x5 bound_ctrl:1
	v_add_f32_dpp v138, v138, v138 row_half_mirror row_mask:0xf bank_mask:0x5 bound_ctrl:1
	v_add_f32_dpp v139, v139, v139 row_half_mirror row_mask:0xf bank_mask:0x5 bound_ctrl:1
	v_add_f32_dpp v136, v140, v140 row_half_mirror row_mask:0xf bank_mask:0xa bound_ctrl:1
	v_add_f32_dpp v137, v141, v141 row_half_mirror row_mask:0xf bank_mask:0xa bound_ctrl:1
	v_add_f32_dpp v138, v142, v142 row_half_mirror row_mask:0xf bank_mask:0xa bound_ctrl:1
	v_add_f32_dpp v139, v144, v144 row_half_mirror row_mask:0xf bank_mask:0xa bound_ctrl:1
	v_add_f32_dpp v136, v136, v136 quad_perm:[2,3,0,1] row_mask:0xf bank_mask:0xf bound_ctrl:1
	v_add_f32_dpp v138, v138, v138 quad_perm:[2,3,0,1] row_mask:0xf bank_mask:0xf bound_ctrl:1
	v_add_f32_dpp v137, v137, v137 quad_perm:[2,3,0,1] row_mask:0xf bank_mask:0xf bound_ctrl:1
	v_add_f32_dpp v139, v139, v139 quad_perm:[2,3,0,1] row_mask:0xf bank_mask:0xf bound_ctrl:1
	v_cndmask_b32_e64 v173, v155, v146, s[28:29]
	v_cndmask_b32_e64 v178, v157, v156, s[28:29]
	v_cndmask_b32_e64 v136, v136, v138, s[24:25]
	v_cndmask_b32_e64 v137, v137, v139, s[24:25]
	v_cndmask_b32_e64 v173, v178, v173, s[24:25]
	v_add_f32_e32 v146, v157, v168
	v_add_f32_dpp v136, v136, v136 quad_perm:[1,0,3,2] row_mask:0xf bank_mask:0xf bound_ctrl:1
	v_add_f32_dpp v137, v137, v137 quad_perm:[1,0,3,2] row_mask:0xf bank_mask:0xf bound_ctrl:1
	v_cndmask_b32_e64 v136, v136, v137, s[28:29]
	v_fmac_f32_e32 v136, 0x3fb8aa3b, v173
	s_nop 1
	v_max_f32_dpp v179, v136, v136 quad_perm:[1,0,3,2] row_mask:0xf bank_mask:0xf bound_ctrl:1
	s_nop 1
	v_max_f32_dpp v180, v179, v179 quad_perm:[2,3,0,1] row_mask:0xf bank_mask:0xf bound_ctrl:1
	v_max_f32_e32 v180, v134, v180
	v_sub_f32_e32 v155, v134, v180
	v_sub_f32_e32 v156, v136, v180
	v_mov_b32_e32 v134, v180
	v_exp_f32_e32 v155, v155
	v_exp_f32_e32 v156, v156
	s_nop 0
	v_mov_b32_dpp v137, v155 row_newbcast:0 row_mask:0xf bank_mask:0xf
	v_mov_b32_dpp v142, v155 row_newbcast:4 row_mask:0xf bank_mask:0xf
	v_mov_b32_dpp v150, v155 row_newbcast:8 row_mask:0xf bank_mask:0xf
	v_mov_b32_dpp v178, v155 row_newbcast:12 row_mask:0xf bank_mask:0xf
	v_add_f32_dpp v157, v156, v156 quad_perm:[1,0,3,2] row_mask:0xf bank_mask:0xf bound_ctrl:1
	v_mov_b32_dpp v138, v156 row_newbcast:0 row_mask:0xf bank_mask:0xf
	v_mov_b32_dpp v139, v156 row_newbcast:1 row_mask:0xf bank_mask:0xf
	v_mov_b32_dpp v140, v156 row_newbcast:2 row_mask:0xf bank_mask:0xf
	v_mov_b32_dpp v141, v156 row_newbcast:3 row_mask:0xf bank_mask:0xf
	v_add_f32_dpp v173, v157, v157 quad_perm:[2,3,0,1] row_mask:0xf bank_mask:0xf bound_ctrl:1
	v_mov_b32_dpp v144, v156 row_newbcast:4 row_mask:0xf bank_mask:0xf
	v_mov_b32_dpp v147, v156 row_newbcast:5 row_mask:0xf bank_mask:0xf
	v_mov_b32_dpp v148, v156 row_newbcast:6 row_mask:0xf bank_mask:0xf
	v_mov_b32_dpp v149, v156 row_newbcast:7 row_mask:0xf bank_mask:0xf
	v_fma_f32 v135, v135, v155, v173
	v_mov_b32_dpp v151, v156 row_newbcast:8 row_mask:0xf bank_mask:0xf
	v_mov_b32_dpp v152, v156 row_newbcast:9 row_mask:0xf bank_mask:0xf
	v_mov_b32_dpp v153, v156 row_newbcast:10 row_mask:0xf bank_mask:0xf
	v_mov_b32_dpp v154, v156 row_newbcast:11 row_mask:0xf bank_mask:0xf
	v_mov_b32_dpp v179, v156 row_newbcast:12 row_mask:0xf bank_mask:0xf
	v_mov_b32_dpp v180, v156 row_newbcast:13 row_mask:0xf bank_mask:0xf
	v_mov_b32_dpp v181, v156 row_newbcast:14 row_mask:0xf bank_mask:0xf
	v_mov_b32_dpp v0, v156 row_newbcast:15 row_mask:0xf bank_mask:0xf
	v_pk_mul_f32 v[118:119], v[118:119], v[136:137] op_sel:[0,1] op_sel_hi:[1,1]
	v_pk_mul_f32 v[120:121], v[120:121], v[136:137] op_sel:[0,1] op_sel_hi:[1,1]
	v_pk_mul_f32 v[122:123], v[122:123], v[142:143] op_sel:[0,0] op_sel_hi:[1,0]
	v_pk_mul_f32 v[124:125], v[124:125], v[142:143] op_sel:[0,0] op_sel_hi:[1,0]
	v_pk_mul_f32 v[126:127], v[126:127], v[150:151] op_sel:[0,0] op_sel_hi:[1,0]
	v_pk_mul_f32 v[128:129], v[128:129], v[150:151] op_sel:[0,0] op_sel_hi:[1,0]
	v_pk_mul_f32 v[130:131], v[130:131], v[178:179] op_sel:[0,0] op_sel_hi:[1,0]
	v_pk_mul_f32 v[132:133], v[132:133], v[178:179] op_sel:[0,0] op_sel_hi:[1,0]
	v_pk_fma_f32 v[118:119], v[138:139], v[2:3], v[118:119] op_sel:[0,0,0] op_sel_hi:[0,1,1]
	v_pk_fma_f32 v[120:121], v[138:139], v[4:5], v[120:121] op_sel:[0,0,0] op_sel_hi:[0,1,1]
	v_pk_fma_f32 v[122:123], v[144:145], v[2:3], v[122:123] op_sel:[0,0,0] op_sel_hi:[0,1,1]
	v_pk_fma_f32 v[124:125], v[144:145], v[4:5], v[124:125] op_sel:[0,0,0] op_sel_hi:[0,1,1]
	v_pk_fma_f32 v[126:127], v[150:151], v[2:3], v[126:127] op_sel:[1,0,0] op_sel_hi:[1,1,1]
	v_pk_fma_f32 v[128:129], v[150:151], v[4:5], v[128:129] op_sel:[1,0,0] op_sel_hi:[1,1,1]
	v_pk_fma_f32 v[130:131], v[178:179], v[2:3], v[130:131] op_sel:[1,0,0] op_sel_hi:[1,1,1]
	v_pk_fma_f32 v[132:133], v[178:179], v[4:5], v[132:133] op_sel:[1,0,0] op_sel_hi:[1,1,1]
	v_pk_fma_f32 v[118:119], v[138:139], v[6:7], v[118:119] op_sel:[1,0,0] op_sel_hi:[1,1,1]
	v_pk_fma_f32 v[120:121], v[138:139], v[8:9], v[120:121] op_sel:[1,0,0] op_sel_hi:[1,1,1]
	v_pk_fma_f32 v[122:123], v[146:147], v[6:7], v[122:123] op_sel:[1,0,0] op_sel_hi:[1,1,1]
	v_pk_fma_f32 v[124:125], v[146:147], v[8:9], v[124:125] op_sel:[1,0,0] op_sel_hi:[1,1,1]
	v_pk_fma_f32 v[126:127], v[152:153], v[6:7], v[126:127] op_sel:[0,0,0] op_sel_hi:[0,1,1]
	v_pk_fma_f32 v[128:129], v[152:153], v[8:9], v[128:129] op_sel:[0,0,0] op_sel_hi:[0,1,1]
	v_pk_fma_f32 v[130:131], v[180:181], v[6:7], v[130:131] op_sel:[0,0,0] op_sel_hi:[0,1,1]
	v_pk_fma_f32 v[132:133], v[180:181], v[8:9], v[132:133] op_sel:[0,0,0] op_sel_hi:[0,1,1]
	v_pk_fma_f32 v[118:119], v[140:141], v[10:11], v[118:119] op_sel:[0,0,0] op_sel_hi:[0,1,1]
	v_pk_fma_f32 v[120:121], v[140:141], v[12:13], v[120:121] op_sel:[0,0,0] op_sel_hi:[0,1,1]
	v_pk_fma_f32 v[122:123], v[148:149], v[10:11], v[122:123] op_sel:[0,0,0] op_sel_hi:[0,1,1]
	v_pk_fma_f32 v[124:125], v[148:149], v[12:13], v[124:125] op_sel:[0,0,0] op_sel_hi:[0,1,1]
	v_pk_fma_f32 v[126:127], v[152:153], v[10:11], v[126:127] op_sel:[1,0,0] op_sel_hi:[1,1,1]
	v_pk_fma_f32 v[128:129], v[152:153], v[12:13], v[128:129] op_sel:[1,0,0] op_sel_hi:[1,1,1]
	v_pk_fma_f32 v[130:131], v[180:181], v[10:11], v[130:131] op_sel:[1,0,0] op_sel_hi:[1,1,1]
	v_pk_fma_f32 v[132:133], v[180:181], v[12:13], v[132:133] op_sel:[1,0,0] op_sel_hi:[1,1,1]
	v_pk_fma_f32 v[118:119], v[140:141], v[14:15], v[118:119] op_sel:[1,0,0] op_sel_hi:[1,1,1]
	v_pk_fma_f32 v[120:121], v[140:141], v[16:17], v[120:121] op_sel:[1,0,0] op_sel_hi:[1,1,1]
	v_pk_fma_f32 v[122:123], v[148:149], v[14:15], v[122:123] op_sel:[1,0,0] op_sel_hi:[1,1,1]
	v_pk_fma_f32 v[124:125], v[148:149], v[16:17], v[124:125] op_sel:[1,0,0] op_sel_hi:[1,1,1]
	v_pk_fma_f32 v[126:127], v[154:155], v[14:15], v[126:127] op_sel:[0,0,0] op_sel_hi:[0,1,1]
	v_pk_fma_f32 v[128:129], v[154:155], v[16:17], v[128:129] op_sel:[0,0,0] op_sel_hi:[0,1,1]
	v_pk_fma_f32 v[130:131], v[0:1], v[14:15], v[130:131] op_sel:[0,0,0] op_sel_hi:[0,1,1]
	v_pk_fma_f32 v[132:133], v[0:1], v[16:17], v[132:133] op_sel:[0,0,0] op_sel_hi:[0,1,1]
	s_waitcnt vmcnt(0)
	s_load_dwordx2 s[0:1], s[42:43], 0x100
	v_lshl_add_u32 v155, s40, 2, v160
	v_lshlrev_b32_e32 v156, 10, v155
	v_lshl_add_u32 v156, v159, 4, v156
	v_lshlrev_b32_e32 v157, 5, v155
	v_lshrrev_b32_e32 v173, 2, v159
	v_lshl_add_u32 v157, v173, 3, v157
	v_and_b32_e32 v173, 3, v159
	v_cmp_eq_u32_e32 vcc, 0, v173
	s_waitcnt lgkmcnt(0)
	s_add_u32 s4, s0, 0x4780000
	s_addc_u32 s5, s1, 0
	s_add_u32 s6, s0, 0x4f80000
	s_addc_u32 s7, s1, 0
	global_store_dwordx4 v156, v[118:121], s[4:5]
	global_store_dwordx4 v156, v[122:125], s[4:5] offset:256
	global_store_dwordx4 v156, v[126:129], s[4:5] offset:512
	global_store_dwordx4 v156, v[130:133], s[4:5] offset:768
	s_and_saveexec_b64 s[2:3], vcc
	global_store_dwordx2 v157, v[134:135], s[6:7]
	s_branch .LBB0_321
